# K-loop load segments: address VALU placed between m0 write and LDS-DMA issue, pad nops removed
# baseline (speedup 1.0000x reference)
; #define PG8_STAGE(bufoff, gbase, voff) do { _Pragma("unroll") for (int _i = 0; _i < 2; ++_i) \
;         __builtin_amdgcn_global_load_lds((const unsigned*)((const char*)(gbase) + (voff)[_i]), (PG8_LAS unsigned*)(lds + (bufoff) + ldsw + _i * 8192), 16, 0, 0); } while (0)
; #define PG8_LDA(dst, b, h) do { _Pragma("unroll") for (int m = 0; m < 4; ++m) _Pragma("unroll") for (int k = 0; k < 2; ++k) dst[m][k] = *(const PG8_LAS bf16x8*)(lds + PG8_SA(b, h) + aoff + m * 2048 + k * 1024); } while (0)
; #define PG8_LDB(dst, b, h) do { _Pragma("unroll") for (int n = 0; n < 2; ++n) _Pragma("unroll") for (int k = 0; k < 2; ++k) dst[n][k] = *(const PG8_LAS bf16x8*)(lds + PG8_SB(b, h) + boff + n * 2048 + k * 1024); } while (0)
; #define PG8_MMA(ai, bj, At, Bt) do { __builtin_amdgcn_s_setprio(1); _Pragma("unroll") for (int m = 0; m < 4; ++m) _Pragma("unroll") for (int n = 0; n < 2; ++n) _Pragma("unroll") for (int k = 0; k < 2; ++k) \
;         acc[ai][bj][m][n] = __builtin_amdgcn_mfma_f32_16x16x32_bf16(Bt[n][k], At[m][k], acc[ai][bj][m][n], 0, 0, 0); __builtin_amdgcn_s_setprio(0); } while (0)
; #define PG8_WAIT_V(n) asm volatile("s_waitcnt vmcnt(" #n ")" ::: "memory")
; #define PG8_WAIT_L(n) asm volatile("s_waitcnt lgkmcnt(" #n ")" ::: "memory")
; template <class Epi, class Sched, bool ALIGN_EPI = false, bool SP2 = false>
; __device__ __forceinline__ void gemm_phase(PG8_LAS unsigned char* lds, const Gemm g, const Sched& S, const Epi& E) {
;     ...
;             const bool last = (t == nt - 2);
;             const char* a1 = cA + (size_t)(t + 1) * kstep;
;             const char* a2 = last ? nA : cA + (size_t)(t + 2) * kstep; const char* b2 = last ? nB : cB + (size_t)(t + 2) * kstep;
;             const char* a3 = a2 + kstep; const char* b3 = b2 + kstep;
;             if (last && has_next) S.a_ready(nxt);
;             if constexpr (SP2) {
;             PG8_LDB(B0, 0, 0); PG8_LDB(B1, 0, 1); PG8_SCHED; PG8_LDA(At, 0, 0); PG8_STAGE(PG8_SA(1, 1), a1 + hstep, voffA);
;             PG8_WAIT_V(8); PG8_WAIT_L(0); PG8_BAR; PG8_MMA(0, 0, At, B0); PG8_MMA(0, 1, At, B1); PG8_BAR; PG8_SCHED;
;             PG8_LDA(At, 0, 1); PG8_STAGE(PG8_SB(0, 0), b2, voffB); PG8_STAGE(PG8_SB(0, 1), b2 + hstep, voffB); PG8_STAGE(PG8_SA(0, 0), a2, voffA);
;             PG8_WAIT_V(8); PG8_WAIT_L(0); PG8_BAR; PG8_MMA(1, 0, At, B0); PG8_MMA(1, 1, At, B1); PG8_BAR; PG8_SCHED;
.LBB0_123:
	s_add_u32 s8, s6, 0xfff80080
	s_addc_u32 s9, s7, -1
	s_add_i32 s43, 0, 0x10000
	s_cmp_eq_u32 s42, 28
	s_cselect_b32 s23, s15, s9
	s_cselect_b32 s22, s24, s8
	s_cselect_b32 s9, s17, s41
	s_cselect_b32 s8, s25, s40
	s_add_i32 s48, 0, 0x14000
	v_add_u32_e32 v172, s43, v165
	v_add_u32_e32 v188, s48, v165
	ds_read_b128 v[156:159], v172
	ds_read_b128 v[160:163], v172 offset:1024
	ds_read_b128 v[168:171], v172 offset:2048
	ds_read_b128 v[172:175], v172 offset:3072
	ds_read_b128 v[176:179], v188
	ds_read_b128 v[180:183], v188 offset:1024
	ds_read_b128 v[184:187], v188 offset:2048
	ds_read_b128 v[188:191], v188 offset:3072
	v_lshl_add_u64 v[228:229], s[6:7], 0, v[152:153]
	s_add_i32 m0, s31, 0xc000
	ds_read_b128 v[192:195], v167
	ds_read_b128 v[196:199], v167 offset:1024
	ds_read_b128 v[200:203], v167 offset:2048
	ds_read_b128 v[204:207], v167 offset:3072
	ds_read_b128 v[208:211], v167 offset:4096
	ds_read_b128 v[212:215], v167 offset:5120
	ds_read_b128 v[216:219], v167 offset:6144
	ds_read_b128 v[224:227], v167 offset:7168
	global_load_lds_dwordx4 v[228:229], off
	s_add_i32 m0, s31, 0xe000
	v_lshl_add_u64 v[228:229], s[6:7], 0, v[154:155]
	global_load_lds_dwordx4 v[228:229], off
	s_waitcnt vmcnt(8) lgkmcnt(0)
	s_setprio 1
	s_barrier
	v_mfma_f32_16x16x32_bf16 v[144:147], v[156:159], v[192:195], v[144:147]
	v_mfma_f32_16x16x32_bf16 v[122:125], v[168:171], v[192:195], v[122:125]
	v_mfma_f32_16x16x32_bf16 v[110:113], v[156:159], v[200:203], v[110:113]
	v_mfma_f32_16x16x32_bf16 v[106:109], v[168:171], v[200:203], v[106:109]
	v_mfma_f32_16x16x32_bf16 v[94:97], v[156:159], v[208:211], v[94:97]
	v_mfma_f32_16x16x32_bf16 v[90:93], v[168:171], v[208:211], v[90:93]
	v_mfma_f32_16x16x32_bf16 v[78:81], v[156:159], v[216:219], v[78:81]
	v_mfma_f32_16x16x32_bf16 v[74:77], v[168:171], v[216:219], v[74:77]
	v_mfma_f32_16x16x32_bf16 v[144:147], v[160:163], v[196:199], v[144:147]
	v_mfma_f32_16x16x32_bf16 v[122:125], v[172:175], v[196:199], v[122:125]
	v_mfma_f32_16x16x32_bf16 v[110:113], v[160:163], v[204:207], v[110:113]
	v_mfma_f32_16x16x32_bf16 v[106:109], v[172:175], v[204:207], v[106:109]
	v_mfma_f32_16x16x32_bf16 v[94:97], v[160:163], v[212:215], v[94:97]
	v_mfma_f32_16x16x32_bf16 v[90:93], v[172:175], v[212:215], v[90:93]
	v_mfma_f32_16x16x32_bf16 v[78:81], v[160:163], v[224:227], v[78:81]
	v_mfma_f32_16x16x32_bf16 v[74:77], v[172:175], v[224:227], v[74:77]
	v_mfma_f32_16x16x32_bf16 v[118:121], v[176:179], v[192:195], v[118:121]
	v_mfma_f32_16x16x32_bf16 v[114:117], v[184:187], v[192:195], v[114:117]
	v_mfma_f32_16x16x32_bf16 v[102:105], v[176:179], v[200:203], v[102:105]
	v_mfma_f32_16x16x32_bf16 v[98:101], v[184:187], v[200:203], v[98:101]
	v_mfma_f32_16x16x32_bf16 v[86:89], v[176:179], v[208:211], v[86:89]
	v_mfma_f32_16x16x32_bf16 v[82:85], v[184:187], v[208:211], v[82:85]
	v_mfma_f32_16x16x32_bf16 v[70:73], v[176:179], v[216:219], v[70:73]
	v_mfma_f32_16x16x32_bf16 v[66:69], v[184:187], v[216:219], v[66:69]
	v_mfma_f32_16x16x32_bf16 v[118:121], v[180:183], v[196:199], v[118:121]
	v_mfma_f32_16x16x32_bf16 v[114:117], v[188:191], v[196:199], v[114:117]
	v_mfma_f32_16x16x32_bf16 v[102:105], v[180:183], v[204:207], v[102:105]
	v_mfma_f32_16x16x32_bf16 v[98:101], v[188:191], v[204:207], v[98:101]
	v_mfma_f32_16x16x32_bf16 v[86:89], v[180:183], v[212:215], v[86:89]
	v_mfma_f32_16x16x32_bf16 v[82:85], v[188:191], v[212:215], v[82:85]
	v_mfma_f32_16x16x32_bf16 v[70:73], v[180:183], v[224:227], v[70:73]
	v_mfma_f32_16x16x32_bf16 v[66:69], v[188:191], v[224:227], v[66:69]
	s_setprio 0
	s_barrier
	s_add_i32 s43, s43, s30
	v_lshl_add_u64 v[228:229], s[8:9], 0, v[0:1]
	s_mov_b32 m0, s43
	ds_read_b128 v[192:195], v167 offset:16384
	ds_read_b128 v[196:199], v167 offset:17408
	ds_read_b128 v[200:203], v167 offset:18432
	ds_read_b128 v[204:207], v167 offset:19456
	ds_read_b128 v[208:211], v167 offset:20480
	ds_read_b128 v[212:215], v167 offset:21504
	ds_read_b128 v[216:219], v167 offset:22528
	ds_read_b128 v[224:227], v167 offset:23552
	global_load_lds_dwordx4 v[228:229], off
	s_add_i32 m0, s43, 0x2000
	s_add_u32 s82, s8, 0x80000
	v_lshl_add_u64 v[230:231], s[8:9], 0, v[126:127]
	s_addc_u32 s83, s9, 0
	s_add_i32 s43, s48, s30
	global_load_lds_dwordx4 v[230:231], off
	v_lshl_add_u64 v[232:233], s[82:83], 0, v[0:1]
	s_mov_b32 m0, s43
	v_lshl_add_u64 v[244:245], s[22:23], 0, v[148:149]
	global_load_lds_dwordx4 v[232:233], off
	s_add_i32 m0, s43, 0x2000
	v_lshl_add_u64 v[232:233], s[82:83], 0, v[126:127]
	global_load_lds_dwordx4 v[232:233], off
	s_mov_b32 m0, s31
	v_lshl_add_u64 v[232:233], s[22:23], 0, v[150:151]
	global_load_lds_dwordx4 v[232:233], off
	s_mov_b32 m0, s34
	s_nop 0
	global_load_lds_dwordx4 v[244:245], off
	s_waitcnt vmcnt(8) lgkmcnt(0)
	s_setprio 1
	s_barrier
; #define PG8_STAGE(bufoff, gbase, voff) do { _Pragma("unroll") for (int _i = 0; _i < 2; ++_i) \
;         __builtin_amdgcn_global_load_lds((const unsigned*)((const char*)(gbase) + (voff)[_i]), (PG8_LAS unsigned*)(lds + (bufoff) + ldsw + _i * 8192), 16, 0, 0); } while (0)
; #define PG8_LDA(dst, b, h) do { _Pragma("unroll") for (int m = 0; m < 4; ++m) _Pragma("unroll") for (int k = 0; k < 2; ++k) dst[m][k] = *(const PG8_LAS bf16x8*)(lds + PG8_SA(b, h) + aoff + m * 2048 + k * 1024); } while (0)
; #define PG8_LDB(dst, b, h) do { _Pragma("unroll") for (int n = 0; n < 2; ++n) _Pragma("unroll") for (int k = 0; k < 2; ++k) dst[n][k] = *(const PG8_LAS bf16x8*)(lds + PG8_SB(b, h) + boff + n * 2048 + k * 1024); } while (0)
; #define PG8_MMA(ai, bj, At, Bt) do { __builtin_amdgcn_s_setprio(1); _Pragma("unroll") for (int m = 0; m < 4; ++m) _Pragma("unroll") for (int n = 0; n < 2; ++n) _Pragma("unroll") for (int k = 0; k < 2; ++k) \
;         acc[ai][bj][m][n] = __builtin_amdgcn_mfma_f32_16x16x32_bf16(Bt[n][k], At[m][k], acc[ai][bj][m][n], 0, 0, 0); __builtin_amdgcn_s_setprio(0); } while (0)
; #define PG8_WAIT_V(n) asm volatile("s_waitcnt vmcnt(" #n ")" ::: "memory")
; #define PG8_WAIT_L(n) asm volatile("s_waitcnt lgkmcnt(" #n ")" ::: "memory")
; #define PG8_BAR __builtin_amdgcn_s_barrier()
; #define PG8_SCHED __builtin_amdgcn_sched_barrier(0)
; template <class Epi, class Sched, bool ALIGN_EPI = false, bool SP2 = false>
; __device__ __forceinline__ void gemm_phase(PG8_LAS unsigned char* lds, const Gemm g, const Sched& S, const Epi& E) {
;     ...
;             PG8_WAIT_V(8); PG8_WAIT_L(0); PG8_BAR; PG8_MMA(1, 0, At, B0); PG8_MMA(1, 1, At, B1); PG8_BAR; PG8_SCHED;
;             PG8_LDB(B0, 1, 0); PG8_LDB(B1, 1, 1); PG8_SCHED; PG8_LDA(At, 1, 0); PG8_STAGE(PG8_SA(0, 1), a2 + hstep, voffA);
;             PG8_WAIT_V(8); PG8_WAIT_L(0); PG8_BAR; PG8_MMA(0, 0, At, B0); PG8_MMA(0, 1, At, B1); PG8_BAR; PG8_SCHED;
	v_mfma_f32_16x16x32_bf16 v[62:65], v[156:159], v[192:195], v[62:65]
	v_mfma_f32_16x16x32_bf16 v[58:61], v[168:171], v[192:195], v[58:61]
	v_mfma_f32_16x16x32_bf16 v[46:49], v[156:159], v[200:203], v[46:49]
	v_mfma_f32_16x16x32_bf16 v[42:45], v[168:171], v[200:203], v[42:45]
	v_mfma_f32_16x16x32_bf16 v[30:33], v[156:159], v[208:211], v[30:33]
	v_mfma_f32_16x16x32_bf16 v[26:29], v[168:171], v[208:211], v[26:29]
	v_mfma_f32_16x16x32_bf16 v[14:17], v[156:159], v[216:219], v[14:17]
	v_mfma_f32_16x16x32_bf16 v[10:13], v[168:171], v[216:219], v[10:13]
	v_mfma_f32_16x16x32_bf16 v[62:65], v[160:163], v[196:199], v[62:65]
	v_mfma_f32_16x16x32_bf16 v[58:61], v[172:175], v[196:199], v[58:61]
	v_mfma_f32_16x16x32_bf16 v[46:49], v[160:163], v[204:207], v[46:49]
	v_mfma_f32_16x16x32_bf16 v[42:45], v[172:175], v[204:207], v[42:45]
	v_mfma_f32_16x16x32_bf16 v[30:33], v[160:163], v[212:215], v[30:33]
	v_mfma_f32_16x16x32_bf16 v[26:29], v[172:175], v[212:215], v[26:29]
	v_mfma_f32_16x16x32_bf16 v[14:17], v[160:163], v[224:227], v[14:17]
	v_mfma_f32_16x16x32_bf16 v[10:13], v[172:175], v[224:227], v[10:13]
	v_mfma_f32_16x16x32_bf16 v[54:57], v[176:179], v[192:195], v[54:57]
	v_mfma_f32_16x16x32_bf16 v[50:53], v[184:187], v[192:195], v[50:53]
	v_mfma_f32_16x16x32_bf16 v[38:41], v[176:179], v[200:203], v[38:41]
	v_mfma_f32_16x16x32_bf16 v[34:37], v[184:187], v[200:203], v[34:37]
	v_mfma_f32_16x16x32_bf16 v[22:25], v[176:179], v[208:211], v[22:25]
	v_mfma_f32_16x16x32_bf16 v[18:21], v[184:187], v[208:211], v[18:21]
	v_mfma_f32_16x16x32_bf16 v[6:9], v[176:179], v[216:219], v[6:9]
	v_mfma_f32_16x16x32_bf16 v[2:5], v[184:187], v[216:219], v[2:5]
	v_mfma_f32_16x16x32_bf16 v[54:57], v[180:183], v[196:199], v[54:57]
	v_mfma_f32_16x16x32_bf16 v[50:53], v[188:191], v[196:199], v[50:53]
	v_mfma_f32_16x16x32_bf16 v[38:41], v[180:183], v[204:207], v[38:41]
	v_mfma_f32_16x16x32_bf16 v[34:37], v[188:191], v[204:207], v[34:37]
	v_mfma_f32_16x16x32_bf16 v[22:25], v[180:183], v[212:215], v[22:25]
	v_mfma_f32_16x16x32_bf16 v[18:21], v[188:191], v[212:215], v[18:21]
	v_mfma_f32_16x16x32_bf16 v[6:9], v[180:183], v[224:227], v[6:9]
	v_mfma_f32_16x16x32_bf16 v[2:5], v[188:191], v[224:227], v[2:5]
	s_setprio 0
	s_barrier
	s_add_i32 s43, 0, 0x18000
	s_add_i32 s48, 0, 0x1c000
	v_add_u32_e32 v172, s43, v165
	v_add_u32_e32 v188, s48, v165
	ds_read_b128 v[156:159], v172
	ds_read_b128 v[160:163], v172 offset:1024
	ds_read_b128 v[168:171], v172 offset:2048
	ds_read_b128 v[172:175], v172 offset:3072
	ds_read_b128 v[176:179], v188
	ds_read_b128 v[180:183], v188 offset:1024
	ds_read_b128 v[184:187], v188 offset:2048
	ds_read_b128 v[188:191], v188 offset:3072
	s_add_u32 s22, s22, 0x80000
	s_addc_u32 s23, s23, 0
	s_mov_b32 m0, s35
	v_lshl_add_u64 v[246:247], s[22:23], 0, v[150:151]
	ds_read_b128 v[192:195], v167 offset:32768
	ds_read_b128 v[196:199], v167 offset:33792
	ds_read_b128 v[200:203], v167 offset:34816
	ds_read_b128 v[204:207], v167 offset:35840
	ds_read_b128 v[208:211], v167 offset:36864
	ds_read_b128 v[212:215], v167 offset:37888
	ds_read_b128 v[216:219], v167 offset:38912
	ds_read_b128 v[224:227], v167 offset:39936
	global_load_lds_dwordx4 v[246:247], off
	s_mov_b32 m0, s36
	v_lshl_add_u64 v[246:247], s[22:23], 0, v[148:149]
	global_load_lds_dwordx4 v[246:247], off
	s_waitcnt vmcnt(8) lgkmcnt(0)
	s_setprio 1
	s_barrier
	v_mfma_f32_16x16x32_bf16 v[144:147], v[156:159], v[192:195], v[144:147]
	v_mfma_f32_16x16x32_bf16 v[122:125], v[168:171], v[192:195], v[122:125]
	v_mfma_f32_16x16x32_bf16 v[110:113], v[156:159], v[200:203], v[110:113]
	v_mfma_f32_16x16x32_bf16 v[106:109], v[168:171], v[200:203], v[106:109]
	v_mfma_f32_16x16x32_bf16 v[94:97], v[156:159], v[208:211], v[94:97]
	v_mfma_f32_16x16x32_bf16 v[90:93], v[168:171], v[208:211], v[90:93]
	v_mfma_f32_16x16x32_bf16 v[78:81], v[156:159], v[216:219], v[78:81]
	v_mfma_f32_16x16x32_bf16 v[74:77], v[168:171], v[216:219], v[74:77]
	v_mfma_f32_16x16x32_bf16 v[144:147], v[160:163], v[196:199], v[144:147]
	v_mfma_f32_16x16x32_bf16 v[122:125], v[172:175], v[196:199], v[122:125]
	v_mfma_f32_16x16x32_bf16 v[110:113], v[160:163], v[204:207], v[110:113]
	v_mfma_f32_16x16x32_bf16 v[106:109], v[172:175], v[204:207], v[106:109]
	v_mfma_f32_16x16x32_bf16 v[94:97], v[160:163], v[212:215], v[94:97]
	v_mfma_f32_16x16x32_bf16 v[90:93], v[172:175], v[212:215], v[90:93]
	v_mfma_f32_16x16x32_bf16 v[78:81], v[160:163], v[224:227], v[78:81]
	v_mfma_f32_16x16x32_bf16 v[74:77], v[172:175], v[224:227], v[74:77]
	v_mfma_f32_16x16x32_bf16 v[118:121], v[176:179], v[192:195], v[118:121]
	v_mfma_f32_16x16x32_bf16 v[114:117], v[184:187], v[192:195], v[114:117]
	v_mfma_f32_16x16x32_bf16 v[102:105], v[176:179], v[200:203], v[102:105]
	v_mfma_f32_16x16x32_bf16 v[98:101], v[184:187], v[200:203], v[98:101]
	v_mfma_f32_16x16x32_bf16 v[86:89], v[176:179], v[208:211], v[86:89]
	v_mfma_f32_16x16x32_bf16 v[82:85], v[184:187], v[208:211], v[82:85]
	v_mfma_f32_16x16x32_bf16 v[70:73], v[176:179], v[216:219], v[70:73]
	v_mfma_f32_16x16x32_bf16 v[66:69], v[184:187], v[216:219], v[66:69]
	v_mfma_f32_16x16x32_bf16 v[118:121], v[180:183], v[196:199], v[118:121]
	v_mfma_f32_16x16x32_bf16 v[114:117], v[188:191], v[196:199], v[114:117]
	v_mfma_f32_16x16x32_bf16 v[102:105], v[180:183], v[204:207], v[102:105]
	v_mfma_f32_16x16x32_bf16 v[98:101], v[188:191], v[204:207], v[98:101]
	v_mfma_f32_16x16x32_bf16 v[86:89], v[180:183], v[212:215], v[86:89]
	v_mfma_f32_16x16x32_bf16 v[82:85], v[188:191], v[212:215], v[82:85]
	v_mfma_f32_16x16x32_bf16 v[70:73], v[180:183], v[224:227], v[70:73]
	v_mfma_f32_16x16x32_bf16 v[66:69], v[188:191], v[224:227], v[66:69]
	s_setprio 0
	s_barrier
; #define PG8_STAGE(bufoff, gbase, voff) do { _Pragma("unroll") for (int _i = 0; _i < 2; ++_i) \
;         __builtin_amdgcn_global_load_lds((const unsigned*)((const char*)(gbase) + (voff)[_i]), (PG8_LAS unsigned*)(lds + (bufoff) + ldsw + _i * 8192), 16, 0, 0); } while (0)
; #define PG8_LDA(dst, b, h) do { _Pragma("unroll") for (int m = 0; m < 4; ++m) _Pragma("unroll") for (int k = 0; k < 2; ++k) dst[m][k] = *(const PG8_LAS bf16x8*)(lds + PG8_SA(b, h) + aoff + m * 2048 + k * 1024); } while (0)
; #define PG8_MMA(ai, bj, At, Bt) do { __builtin_amdgcn_s_setprio(1); _Pragma("unroll") for (int m = 0; m < 4; ++m) _Pragma("unroll") for (int n = 0; n < 2; ++n) _Pragma("unroll") for (int k = 0; k < 2; ++k) \
;         acc[ai][bj][m][n] = __builtin_amdgcn_mfma_f32_16x16x32_bf16(Bt[n][k], At[m][k], acc[ai][bj][m][n], 0, 0, 0); __builtin_amdgcn_s_setprio(0); } while (0)
; #define PG8_WAIT_V(n) asm volatile("s_waitcnt vmcnt(" #n ")" ::: "memory")
; #define PG8_WAIT_L(n) asm volatile("s_waitcnt lgkmcnt(" #n ")" ::: "memory")
; #define PG8_BAR __builtin_amdgcn_s_barrier()
; #define PG8_SCHED __builtin_amdgcn_sched_barrier(0)
; template <class Epi, class Sched, bool ALIGN_EPI = false, bool SP2 = false>
; __device__ __forceinline__ void gemm_phase(PG8_LAS unsigned char* lds, const Gemm g, const Sched& S, const Epi& E) {
;     ...
;             PG8_LDA(At, 1, 1); PG8_STAGE(PG8_SB(1, 0), b3, voffB); PG8_STAGE(PG8_SB(1, 1), b3 + hstep, voffB); PG8_STAGE(PG8_SA(1, 0), a3, voffA);
;             PG8_WAIT_V(8); PG8_WAIT_L(0); PG8_BAR; PG8_MMA(1, 0, At, B0); PG8_MMA(1, 1, At, B1); PG8_BAR; PG8_SCHED;
;     ...
;         if constexpr (ALIGN_EPI) { if (wr == 0) PG8_BAR; }
	s_add_i32 s22, s43, s30
	v_lshl_add_u64 v[228:229], v[228:229], 0, s[64:65]
	s_mov_b32 m0, s22
	ds_read_b128 v[192:195], v167 offset:49152
	ds_read_b128 v[196:199], v167 offset:50176
	ds_read_b128 v[200:203], v167 offset:51200
	ds_read_b128 v[204:207], v167 offset:52224
	ds_read_b128 v[208:211], v167 offset:53248
	ds_read_b128 v[212:215], v167 offset:54272
	ds_read_b128 v[216:219], v167 offset:55296
	ds_read_b128 v[224:227], v167 offset:56320
	global_load_lds_dwordx4 v[228:229], off
	s_add_i32 m0, s22, 0x2000
	s_add_u32 s8, s8, 0x80080
	v_lshl_add_u64 v[228:229], v[230:231], 0, s[64:65]
	s_addc_u32 s9, s9, 0
	s_add_i32 s22, s48, s30
	global_load_lds_dwordx4 v[228:229], off
	s_mov_b32 m0, s22
	v_lshl_add_u64 v[228:229], s[8:9], 0, v[0:1]
	global_load_lds_dwordx4 v[228:229], off
	s_add_i32 m0, s22, 0x2000
	v_lshl_add_u64 v[228:229], s[8:9], 0, v[126:127]
	global_load_lds_dwordx4 v[228:229], off
	s_mov_b32 m0, s37
	v_lshl_add_u64 v[228:229], v[232:233], 0, s[64:65]
	global_load_lds_dwordx4 v[228:229], off
	s_mov_b32 m0, s76
	v_lshl_add_u64 v[228:229], v[244:245], 0, s[64:65]
	global_load_lds_dwordx4 v[228:229], off
	s_waitcnt vmcnt(8) lgkmcnt(0)
	s_setprio 1
	s_barrier
	v_mfma_f32_16x16x32_bf16 v[62:65], v[156:159], v[192:195], v[62:65]
	v_mfma_f32_16x16x32_bf16 v[58:61], v[168:171], v[192:195], v[58:61]
	v_mfma_f32_16x16x32_bf16 v[46:49], v[156:159], v[200:203], v[46:49]
	v_mfma_f32_16x16x32_bf16 v[42:45], v[168:171], v[200:203], v[42:45]
	v_mfma_f32_16x16x32_bf16 v[30:33], v[156:159], v[208:211], v[30:33]
	v_mfma_f32_16x16x32_bf16 v[26:29], v[168:171], v[208:211], v[26:29]
	v_mfma_f32_16x16x32_bf16 v[14:17], v[156:159], v[216:219], v[14:17]
	v_mfma_f32_16x16x32_bf16 v[10:13], v[168:171], v[216:219], v[10:13]
	v_mfma_f32_16x16x32_bf16 v[62:65], v[160:163], v[196:199], v[62:65]
	v_mfma_f32_16x16x32_bf16 v[58:61], v[172:175], v[196:199], v[58:61]
	v_mfma_f32_16x16x32_bf16 v[46:49], v[160:163], v[204:207], v[46:49]
	v_mfma_f32_16x16x32_bf16 v[42:45], v[172:175], v[204:207], v[42:45]
	v_mfma_f32_16x16x32_bf16 v[30:33], v[160:163], v[212:215], v[30:33]
	v_mfma_f32_16x16x32_bf16 v[26:29], v[172:175], v[212:215], v[26:29]
	v_mfma_f32_16x16x32_bf16 v[14:17], v[160:163], v[224:227], v[14:17]
	v_mfma_f32_16x16x32_bf16 v[10:13], v[172:175], v[224:227], v[10:13]
	v_mfma_f32_16x16x32_bf16 v[54:57], v[176:179], v[192:195], v[54:57]
	v_mfma_f32_16x16x32_bf16 v[50:53], v[184:187], v[192:195], v[50:53]
	v_mfma_f32_16x16x32_bf16 v[38:41], v[176:179], v[200:203], v[38:41]
	v_mfma_f32_16x16x32_bf16 v[34:37], v[184:187], v[200:203], v[34:37]
	v_mfma_f32_16x16x32_bf16 v[22:25], v[176:179], v[208:211], v[22:25]
	v_mfma_f32_16x16x32_bf16 v[18:21], v[184:187], v[208:211], v[18:21]
	v_mfma_f32_16x16x32_bf16 v[6:9], v[176:179], v[216:219], v[6:9]
	v_mfma_f32_16x16x32_bf16 v[2:5], v[184:187], v[216:219], v[2:5]
	v_mfma_f32_16x16x32_bf16 v[54:57], v[180:183], v[196:199], v[54:57]
	v_mfma_f32_16x16x32_bf16 v[50:53], v[188:191], v[196:199], v[50:53]
	v_mfma_f32_16x16x32_bf16 v[38:41], v[180:183], v[204:207], v[38:41]
	v_mfma_f32_16x16x32_bf16 v[34:37], v[188:191], v[204:207], v[34:37]
	v_mfma_f32_16x16x32_bf16 v[22:25], v[180:183], v[212:215], v[22:25]
	v_mfma_f32_16x16x32_bf16 v[18:21], v[188:191], v[212:215], v[18:21]
	v_mfma_f32_16x16x32_bf16 v[6:9], v[180:183], v[224:227], v[6:9]
	v_mfma_f32_16x16x32_bf16 v[2:5], v[188:191], v[224:227], v[2:5]
	s_setprio 0
	s_barrier
	s_add_i32 s42, s42, 2
	s_add_u32 s6, s6, 0x100
	s_addc_u32 s7, s7, 0
	s_add_u32 s40, s40, 0x100
	s_addc_u32 s41, s41, 0
	s_cmp_gt_u32 s42, 29
	s_cbranch_scc0 .LBB0_123
	s_and_b64 vcc, exec, s[12:13]
	s_cbranch_vccz .LBB0_126
	s_barrier

; #define PG8_STAGE(bufoff, gbase, voff) do { _Pragma("unroll") for (int _i = 0; _i < 2; ++_i) \
;         __builtin_amdgcn_global_load_lds((const unsigned*)((const char*)(gbase) + (voff)[_i]), (PG8_LAS unsigned*)(lds + (bufoff) + ldsw + _i * 8192), 16, 0, 0); } while (0)
; #define PG8_LDA(dst, b, h) do { _Pragma("unroll") for (int m = 0; m < 4; ++m) _Pragma("unroll") for (int k = 0; k < 2; ++k) dst[m][k] = *(const PG8_LAS bf16x8*)(lds + PG8_SA(b, h) + aoff + m * 2048 + k * 1024); } while (0)
; #define PG8_LDB(dst, b, h) do { _Pragma("unroll") for (int n = 0; n < 2; ++n) _Pragma("unroll") for (int k = 0; k < 2; ++k) dst[n][k] = *(const PG8_LAS bf16x8*)(lds + PG8_SB(b, h) + boff + n * 2048 + k * 1024); } while (0)
; #define PG8_MMA(ai, bj, At, Bt) do { __builtin_amdgcn_s_setprio(1); _Pragma("unroll") for (int m = 0; m < 4; ++m) _Pragma("unroll") for (int n = 0; n < 2; ++n) _Pragma("unroll") for (int k = 0; k < 2; ++k) \
;         acc[ai][bj][m][n] = __builtin_amdgcn_mfma_f32_16x16x32_bf16(Bt[n][k], At[m][k], acc[ai][bj][m][n], 0, 0, 0); __builtin_amdgcn_s_setprio(0); } while (0)
; #define PG8_WAIT_V(n) asm volatile("s_waitcnt vmcnt(" #n ")" ::: "memory")
; #define PG8_WAIT_L(n) asm volatile("s_waitcnt lgkmcnt(" #n ")" ::: "memory")
; template <class Epi, class Sched, bool ALIGN_EPI = false, bool SP2 = false>
; __device__ __forceinline__ void gemm_phase(PG8_LAS unsigned char* lds, const Gemm g, const Sched& S, const Epi& E) {
;     ...
;             const bool last = (t == nt - 2);
;             const char* a1 = cA + (size_t)(t + 1) * kstep;
;             const char* a2 = last ? nA : cA + (size_t)(t + 2) * kstep; const char* b2 = last ? nB : cB + (size_t)(t + 2) * kstep;
;             const char* a3 = a2 + kstep; const char* b3 = b2 + kstep;
;             if (last && has_next) S.a_ready(nxt);
;             if constexpr (SP2) {
;             PG8_LDB(B0, 0, 0); PG8_LDB(B1, 0, 1); PG8_SCHED; PG8_LDA(At, 0, 0); PG8_STAGE(PG8_SA(1, 1), a1 + hstep, voffA);
;             PG8_WAIT_V(8); PG8_WAIT_L(0); PG8_BAR; PG8_MMA(0, 0, At, B0); PG8_MMA(0, 1, At, B1); PG8_BAR; PG8_SCHED;
;             PG8_LDA(At, 0, 1); PG8_STAGE(PG8_SB(0, 0), b2, voffB); PG8_STAGE(PG8_SB(0, 1), b2 + hstep, voffB); PG8_STAGE(PG8_SA(0, 0), a2, voffA);
;             PG8_WAIT_V(8); PG8_WAIT_L(0); PG8_BAR; PG8_MMA(1, 0, At, B0); PG8_MMA(1, 1, At, B1); PG8_BAR; PG8_SCHED;
.LBB0_307:
	s_add_u32 s4, s42, s0
	s_addc_u32 s5, s43, s1
	s_add_u32 s4, s4, 0x2cc00100
	s_addc_u32 s5, s5, 0
	s_add_u32 s20, s48, s0
	s_addc_u32 s21, s67, s1
	s_add_i32 s22, 0, 0x10000
	s_cmpk_eq_i32 s0, 0xf00
	s_cselect_b32 s7, s55, s5
	s_cselect_b32 s6, s54, s4
	s_cselect_b32 s5, s53, s21
	s_cselect_b32 s4, s52, s20
	s_add_i32 s23, 0, 0x14000
	v_add_u32_e32 v172, s22, v158
	v_add_u32_e32 v188, s23, v158
	ds_read_b128 v[160:163], v172
	ds_read_b128 v[164:167], v172 offset:1024
	ds_read_b128 v[168:171], v172 offset:2048
	ds_read_b128 v[172:175], v172 offset:3072
	ds_read_b128 v[176:179], v188
	ds_read_b128 v[180:183], v188 offset:1024
	ds_read_b128 v[184:187], v188 offset:2048
	ds_read_b128 v[188:191], v188 offset:3072
	v_lshl_add_u64 v[228:229], v[152:153], 0, s[0:1]
	s_add_i32 m0, s12, 0xc000
	ds_read_b128 v[192:195], v159
	ds_read_b128 v[196:199], v159 offset:1024
	ds_read_b128 v[200:203], v159 offset:2048
	ds_read_b128 v[204:207], v159 offset:3072
	ds_read_b128 v[208:211], v159 offset:4096
	ds_read_b128 v[212:215], v159 offset:5120
	ds_read_b128 v[216:219], v159 offset:6144
	ds_read_b128 v[224:227], v159 offset:7168
	global_load_lds_dwordx4 v[228:229], off
	s_add_i32 m0, s12, 0xe000
	v_lshl_add_u64 v[228:229], v[154:155], 0, s[0:1]
	global_load_lds_dwordx4 v[228:229], off
	s_waitcnt vmcnt(8) lgkmcnt(0)
	s_setprio 1
	s_barrier
	v_mfma_f32_16x16x32_bf16 v[144:147], v[160:163], v[192:195], v[144:147]
	v_mfma_f32_16x16x32_bf16 v[122:125], v[168:171], v[192:195], v[122:125]
	v_mfma_f32_16x16x32_bf16 v[118:121], v[160:163], v[200:203], v[118:121]
	v_mfma_f32_16x16x32_bf16 v[114:117], v[168:171], v[200:203], v[114:117]
	v_mfma_f32_16x16x32_bf16 v[102:105], v[160:163], v[208:211], v[102:105]
	v_mfma_f32_16x16x32_bf16 v[98:101], v[168:171], v[208:211], v[98:101]
	v_mfma_f32_16x16x32_bf16 v[86:89], v[160:163], v[216:219], v[86:89]
	v_mfma_f32_16x16x32_bf16 v[82:85], v[168:171], v[216:219], v[82:85]
	v_mfma_f32_16x16x32_bf16 v[144:147], v[164:167], v[196:199], v[144:147]
	v_mfma_f32_16x16x32_bf16 v[122:125], v[172:175], v[196:199], v[122:125]
	v_mfma_f32_16x16x32_bf16 v[118:121], v[164:167], v[204:207], v[118:121]
	v_mfma_f32_16x16x32_bf16 v[114:117], v[172:175], v[204:207], v[114:117]
	v_mfma_f32_16x16x32_bf16 v[102:105], v[164:167], v[212:215], v[102:105]
	v_mfma_f32_16x16x32_bf16 v[98:101], v[172:175], v[212:215], v[98:101]
	v_mfma_f32_16x16x32_bf16 v[86:89], v[164:167], v[224:227], v[86:89]
	v_mfma_f32_16x16x32_bf16 v[82:85], v[172:175], v[224:227], v[82:85]
	v_mfma_f32_16x16x32_bf16 v[110:113], v[176:179], v[192:195], v[110:113]
	v_mfma_f32_16x16x32_bf16 v[106:109], v[184:187], v[192:195], v[106:109]
	v_mfma_f32_16x16x32_bf16 v[94:97], v[176:179], v[200:203], v[94:97]
	v_mfma_f32_16x16x32_bf16 v[90:93], v[184:187], v[200:203], v[90:93]
	v_mfma_f32_16x16x32_bf16 v[78:81], v[176:179], v[208:211], v[78:81]
	v_mfma_f32_16x16x32_bf16 v[74:77], v[184:187], v[208:211], v[74:77]
	v_mfma_f32_16x16x32_bf16 v[70:73], v[176:179], v[216:219], v[70:73]
	v_mfma_f32_16x16x32_bf16 v[66:69], v[184:187], v[216:219], v[66:69]
	v_mfma_f32_16x16x32_bf16 v[110:113], v[180:183], v[196:199], v[110:113]
	v_mfma_f32_16x16x32_bf16 v[106:109], v[188:191], v[196:199], v[106:109]
	v_mfma_f32_16x16x32_bf16 v[94:97], v[180:183], v[204:207], v[94:97]
	v_mfma_f32_16x16x32_bf16 v[90:93], v[188:191], v[204:207], v[90:93]
	v_mfma_f32_16x16x32_bf16 v[78:81], v[180:183], v[212:215], v[78:81]
	v_mfma_f32_16x16x32_bf16 v[74:77], v[188:191], v[212:215], v[74:77]
	v_mfma_f32_16x16x32_bf16 v[70:73], v[180:183], v[224:227], v[70:73]
	v_mfma_f32_16x16x32_bf16 v[66:69], v[188:191], v[224:227], v[66:69]
	s_setprio 0
	s_barrier
	s_add_i32 s20, s22, s9
	v_lshl_add_u64 v[228:229], s[4:5], 0, v[0:1]
	s_mov_b32 m0, s20
	ds_read_b128 v[192:195], v159 offset:16384
	ds_read_b128 v[196:199], v159 offset:17408
	ds_read_b128 v[200:203], v159 offset:18432
	ds_read_b128 v[204:207], v159 offset:19456
	ds_read_b128 v[208:211], v159 offset:20480
	ds_read_b128 v[212:215], v159 offset:21504
	ds_read_b128 v[216:219], v159 offset:22528
	ds_read_b128 v[224:227], v159 offset:23552
	global_load_lds_dwordx4 v[228:229], off
	s_add_i32 m0, s20, 0x2000
	s_add_u32 s20, s4, 0x80000
	v_lshl_add_u64 v[230:231], s[4:5], 0, v[126:127]
	s_addc_u32 s21, s5, 0
	s_add_i32 s22, s23, s9
	global_load_lds_dwordx4 v[230:231], off
	v_lshl_add_u64 v[232:233], s[20:21], 0, v[0:1]
	s_mov_b32 m0, s22
	v_lshl_add_u64 v[244:245], s[6:7], 0, v[148:149]
	global_load_lds_dwordx4 v[232:233], off
	s_add_i32 m0, s22, 0x2000
	v_lshl_add_u64 v[232:233], s[20:21], 0, v[126:127]
	global_load_lds_dwordx4 v[232:233], off
	s_mov_b32 m0, s12
	v_lshl_add_u64 v[232:233], s[6:7], 0, v[150:151]
	global_load_lds_dwordx4 v[232:233], off
	s_mov_b32 m0, s13
	s_nop 0
	global_load_lds_dwordx4 v[244:245], off
	s_waitcnt vmcnt(8) lgkmcnt(0)
	s_setprio 1
	s_barrier
; #define PG8_STAGE(bufoff, gbase, voff) do { _Pragma("unroll") for (int _i = 0; _i < 2; ++_i) \
;         __builtin_amdgcn_global_load_lds((const unsigned*)((const char*)(gbase) + (voff)[_i]), (PG8_LAS unsigned*)(lds + (bufoff) + ldsw + _i * 8192), 16, 0, 0); } while (0)
; #define PG8_LDA(dst, b, h) do { _Pragma("unroll") for (int m = 0; m < 4; ++m) _Pragma("unroll") for (int k = 0; k < 2; ++k) dst[m][k] = *(const PG8_LAS bf16x8*)(lds + PG8_SA(b, h) + aoff + m * 2048 + k * 1024); } while (0)
; #define PG8_LDB(dst, b, h) do { _Pragma("unroll") for (int n = 0; n < 2; ++n) _Pragma("unroll") for (int k = 0; k < 2; ++k) dst[n][k] = *(const PG8_LAS bf16x8*)(lds + PG8_SB(b, h) + boff + n * 2048 + k * 1024); } while (0)
; #define PG8_MMA(ai, bj, At, Bt) do { __builtin_amdgcn_s_setprio(1); _Pragma("unroll") for (int m = 0; m < 4; ++m) _Pragma("unroll") for (int n = 0; n < 2; ++n) _Pragma("unroll") for (int k = 0; k < 2; ++k) \
;         acc[ai][bj][m][n] = __builtin_amdgcn_mfma_f32_16x16x32_bf16(Bt[n][k], At[m][k], acc[ai][bj][m][n], 0, 0, 0); __builtin_amdgcn_s_setprio(0); } while (0)
; #define PG8_WAIT_V(n) asm volatile("s_waitcnt vmcnt(" #n ")" ::: "memory")
; #define PG8_WAIT_L(n) asm volatile("s_waitcnt lgkmcnt(" #n ")" ::: "memory")
; #define PG8_BAR __builtin_amdgcn_s_barrier()
; #define PG8_SCHED __builtin_amdgcn_sched_barrier(0)
; template <class Epi, class Sched, bool ALIGN_EPI = false, bool SP2 = false>
; __device__ __forceinline__ void gemm_phase(PG8_LAS unsigned char* lds, const Gemm g, const Sched& S, const Epi& E) {
;     ...
;             PG8_WAIT_V(8); PG8_WAIT_L(0); PG8_BAR; PG8_MMA(1, 0, At, B0); PG8_MMA(1, 1, At, B1); PG8_BAR; PG8_SCHED;
;             PG8_LDB(B0, 1, 0); PG8_LDB(B1, 1, 1); PG8_SCHED; PG8_LDA(At, 1, 0); PG8_STAGE(PG8_SA(0, 1), a2 + hstep, voffA);
;             PG8_WAIT_V(8); PG8_WAIT_L(0); PG8_BAR; PG8_MMA(0, 0, At, B0); PG8_MMA(0, 1, At, B1); PG8_BAR; PG8_SCHED;
	v_mfma_f32_16x16x32_bf16 v[62:65], v[160:163], v[192:195], v[62:65]
	v_mfma_f32_16x16x32_bf16 v[58:61], v[168:171], v[192:195], v[58:61]
	v_mfma_f32_16x16x32_bf16 v[54:57], v[160:163], v[200:203], v[54:57]
	v_mfma_f32_16x16x32_bf16 v[50:53], v[168:171], v[200:203], v[50:53]
	v_mfma_f32_16x16x32_bf16 v[38:41], v[160:163], v[208:211], v[38:41]
	v_mfma_f32_16x16x32_bf16 v[34:37], v[168:171], v[208:211], v[34:37]
	v_mfma_f32_16x16x32_bf16 v[22:25], v[160:163], v[216:219], v[22:25]
	v_mfma_f32_16x16x32_bf16 v[18:21], v[168:171], v[216:219], v[18:21]
	v_mfma_f32_16x16x32_bf16 v[62:65], v[164:167], v[196:199], v[62:65]
	v_mfma_f32_16x16x32_bf16 v[58:61], v[172:175], v[196:199], v[58:61]
	v_mfma_f32_16x16x32_bf16 v[54:57], v[164:167], v[204:207], v[54:57]
	v_mfma_f32_16x16x32_bf16 v[50:53], v[172:175], v[204:207], v[50:53]
	v_mfma_f32_16x16x32_bf16 v[38:41], v[164:167], v[212:215], v[38:41]
	v_mfma_f32_16x16x32_bf16 v[34:37], v[172:175], v[212:215], v[34:37]
	v_mfma_f32_16x16x32_bf16 v[22:25], v[164:167], v[224:227], v[22:25]
	v_mfma_f32_16x16x32_bf16 v[18:21], v[172:175], v[224:227], v[18:21]
	v_mfma_f32_16x16x32_bf16 v[46:49], v[176:179], v[192:195], v[46:49]
	v_mfma_f32_16x16x32_bf16 v[42:45], v[184:187], v[192:195], v[42:45]
	v_mfma_f32_16x16x32_bf16 v[30:33], v[176:179], v[200:203], v[30:33]
	v_mfma_f32_16x16x32_bf16 v[26:29], v[184:187], v[200:203], v[26:29]
	v_mfma_f32_16x16x32_bf16 v[14:17], v[176:179], v[208:211], v[14:17]
	v_mfma_f32_16x16x32_bf16 v[10:13], v[184:187], v[208:211], v[10:13]
	v_mfma_f32_16x16x32_bf16 v[6:9], v[176:179], v[216:219], v[6:9]
	v_mfma_f32_16x16x32_bf16 v[2:5], v[184:187], v[216:219], v[2:5]
	v_mfma_f32_16x16x32_bf16 v[46:49], v[180:183], v[196:199], v[46:49]
	v_mfma_f32_16x16x32_bf16 v[42:45], v[188:191], v[196:199], v[42:45]
	v_mfma_f32_16x16x32_bf16 v[30:33], v[180:183], v[204:207], v[30:33]
	v_mfma_f32_16x16x32_bf16 v[26:29], v[188:191], v[204:207], v[26:29]
	v_mfma_f32_16x16x32_bf16 v[14:17], v[180:183], v[212:215], v[14:17]
	v_mfma_f32_16x16x32_bf16 v[10:13], v[188:191], v[212:215], v[10:13]
	v_mfma_f32_16x16x32_bf16 v[6:9], v[180:183], v[224:227], v[6:9]
	v_mfma_f32_16x16x32_bf16 v[2:5], v[188:191], v[224:227], v[2:5]
	s_setprio 0
	s_barrier
	s_add_i32 s20, 0, 0x18000
	s_add_i32 s21, 0, 0x1c000
	v_add_u32_e32 v172, s20, v158
	v_add_u32_e32 v188, s21, v158
	ds_read_b128 v[160:163], v172
	ds_read_b128 v[164:167], v172 offset:1024
	ds_read_b128 v[168:171], v172 offset:2048
	ds_read_b128 v[172:175], v172 offset:3072
	ds_read_b128 v[176:179], v188
	ds_read_b128 v[180:183], v188 offset:1024
	ds_read_b128 v[184:187], v188 offset:2048
	ds_read_b128 v[188:191], v188 offset:3072
	s_add_u32 s6, s6, 0x80000
	s_addc_u32 s7, s7, 0
	s_mov_b32 m0, s14
	v_lshl_add_u64 v[246:247], s[6:7], 0, v[150:151]
	ds_read_b128 v[192:195], v159 offset:32768
	ds_read_b128 v[196:199], v159 offset:33792
	ds_read_b128 v[200:203], v159 offset:34816
	ds_read_b128 v[204:207], v159 offset:35840
	ds_read_b128 v[208:211], v159 offset:36864
	ds_read_b128 v[212:215], v159 offset:37888
	ds_read_b128 v[216:219], v159 offset:38912
	ds_read_b128 v[224:227], v159 offset:39936
	global_load_lds_dwordx4 v[246:247], off
	s_mov_b32 m0, s15
	v_lshl_add_u64 v[246:247], s[6:7], 0, v[148:149]
	global_load_lds_dwordx4 v[246:247], off
	s_waitcnt vmcnt(8) lgkmcnt(0)
	s_setprio 1
	s_barrier
	v_mfma_f32_16x16x32_bf16 v[144:147], v[160:163], v[192:195], v[144:147]
	v_mfma_f32_16x16x32_bf16 v[122:125], v[168:171], v[192:195], v[122:125]
	v_mfma_f32_16x16x32_bf16 v[118:121], v[160:163], v[200:203], v[118:121]
	v_mfma_f32_16x16x32_bf16 v[114:117], v[168:171], v[200:203], v[114:117]
	v_mfma_f32_16x16x32_bf16 v[102:105], v[160:163], v[208:211], v[102:105]
	v_mfma_f32_16x16x32_bf16 v[98:101], v[168:171], v[208:211], v[98:101]
	v_mfma_f32_16x16x32_bf16 v[86:89], v[160:163], v[216:219], v[86:89]
	v_mfma_f32_16x16x32_bf16 v[82:85], v[168:171], v[216:219], v[82:85]
	v_mfma_f32_16x16x32_bf16 v[144:147], v[164:167], v[196:199], v[144:147]
	v_mfma_f32_16x16x32_bf16 v[122:125], v[172:175], v[196:199], v[122:125]
	v_mfma_f32_16x16x32_bf16 v[118:121], v[164:167], v[204:207], v[118:121]
	v_mfma_f32_16x16x32_bf16 v[114:117], v[172:175], v[204:207], v[114:117]
	v_mfma_f32_16x16x32_bf16 v[102:105], v[164:167], v[212:215], v[102:105]
	v_mfma_f32_16x16x32_bf16 v[98:101], v[172:175], v[212:215], v[98:101]
	v_mfma_f32_16x16x32_bf16 v[86:89], v[164:167], v[224:227], v[86:89]
	v_mfma_f32_16x16x32_bf16 v[82:85], v[172:175], v[224:227], v[82:85]
	v_mfma_f32_16x16x32_bf16 v[110:113], v[176:179], v[192:195], v[110:113]
	v_mfma_f32_16x16x32_bf16 v[106:109], v[184:187], v[192:195], v[106:109]
	v_mfma_f32_16x16x32_bf16 v[94:97], v[176:179], v[200:203], v[94:97]
	v_mfma_f32_16x16x32_bf16 v[90:93], v[184:187], v[200:203], v[90:93]
	v_mfma_f32_16x16x32_bf16 v[78:81], v[176:179], v[208:211], v[78:81]
	v_mfma_f32_16x16x32_bf16 v[74:77], v[184:187], v[208:211], v[74:77]
	v_mfma_f32_16x16x32_bf16 v[70:73], v[176:179], v[216:219], v[70:73]
	v_mfma_f32_16x16x32_bf16 v[66:69], v[184:187], v[216:219], v[66:69]
	v_mfma_f32_16x16x32_bf16 v[110:113], v[180:183], v[196:199], v[110:113]
	v_mfma_f32_16x16x32_bf16 v[106:109], v[188:191], v[196:199], v[106:109]
	v_mfma_f32_16x16x32_bf16 v[94:97], v[180:183], v[204:207], v[94:97]
	v_mfma_f32_16x16x32_bf16 v[90:93], v[188:191], v[204:207], v[90:93]
	v_mfma_f32_16x16x32_bf16 v[78:81], v[180:183], v[212:215], v[78:81]
	v_mfma_f32_16x16x32_bf16 v[74:77], v[188:191], v[212:215], v[74:77]
	v_mfma_f32_16x16x32_bf16 v[70:73], v[180:183], v[224:227], v[70:73]
	v_mfma_f32_16x16x32_bf16 v[66:69], v[188:191], v[224:227], v[66:69]
	s_setprio 0
	s_barrier
; #define PG8_STAGE(bufoff, gbase, voff) do { _Pragma("unroll") for (int _i = 0; _i < 2; ++_i) \
;         __builtin_amdgcn_global_load_lds((const unsigned*)((const char*)(gbase) + (voff)[_i]), (PG8_LAS unsigned*)(lds + (bufoff) + ldsw + _i * 8192), 16, 0, 0); } while (0)
; #define PG8_LDA(dst, b, h) do { _Pragma("unroll") for (int m = 0; m < 4; ++m) _Pragma("unroll") for (int k = 0; k < 2; ++k) dst[m][k] = *(const PG8_LAS bf16x8*)(lds + PG8_SA(b, h) + aoff + m * 2048 + k * 1024); } while (0)
; #define PG8_MMA(ai, bj, At, Bt) do { __builtin_amdgcn_s_setprio(1); _Pragma("unroll") for (int m = 0; m < 4; ++m) _Pragma("unroll") for (int n = 0; n < 2; ++n) _Pragma("unroll") for (int k = 0; k < 2; ++k) \
;         acc[ai][bj][m][n] = __builtin_amdgcn_mfma_f32_16x16x32_bf16(Bt[n][k], At[m][k], acc[ai][bj][m][n], 0, 0, 0); __builtin_amdgcn_s_setprio(0); } while (0)
; #define PG8_WAIT_V(n) asm volatile("s_waitcnt vmcnt(" #n ")" ::: "memory")
; #define PG8_WAIT_L(n) asm volatile("s_waitcnt lgkmcnt(" #n ")" ::: "memory")
; #define PG8_BAR __builtin_amdgcn_s_barrier()
; #define PG8_SCHED __builtin_amdgcn_sched_barrier(0)
; template <class Epi, class Sched, bool ALIGN_EPI = false, bool SP2 = false>
; __device__ __forceinline__ void gemm_phase(PG8_LAS unsigned char* lds, const Gemm g, const Sched& S, const Epi& E) {
;     ...
;             PG8_LDA(At, 1, 1); PG8_STAGE(PG8_SB(1, 0), b3, voffB); PG8_STAGE(PG8_SB(1, 1), b3 + hstep, voffB); PG8_STAGE(PG8_SA(1, 0), a3, voffA);
;             PG8_WAIT_V(8); PG8_WAIT_L(0); PG8_BAR; PG8_MMA(1, 0, At, B0); PG8_MMA(1, 1, At, B1); PG8_BAR; PG8_SCHED;
;     ...
;         if constexpr (ALIGN_EPI) { if (wr == 0) PG8_BAR; }
	s_add_i32 s6, s20, s9
	v_lshl_add_u64 v[228:229], v[228:229], 0, s[64:65]
	s_mov_b32 m0, s6
	ds_read_b128 v[192:195], v159 offset:49152
	ds_read_b128 v[196:199], v159 offset:50176
	ds_read_b128 v[200:203], v159 offset:51200
	ds_read_b128 v[204:207], v159 offset:52224
	ds_read_b128 v[208:211], v159 offset:53248
	ds_read_b128 v[212:215], v159 offset:54272
	ds_read_b128 v[216:219], v159 offset:55296
	ds_read_b128 v[224:227], v159 offset:56320
	global_load_lds_dwordx4 v[228:229], off
	s_add_i32 m0, s6, 0x2000
	s_add_u32 s4, s4, 0x80080
	v_lshl_add_u64 v[228:229], v[230:231], 0, s[64:65]
	s_addc_u32 s5, s5, 0
	s_add_i32 s6, s21, s9
	global_load_lds_dwordx4 v[228:229], off
	s_mov_b32 m0, s6
	v_lshl_add_u64 v[228:229], s[4:5], 0, v[0:1]
	global_load_lds_dwordx4 v[228:229], off
	s_add_i32 m0, s6, 0x2000
	v_lshl_add_u64 v[228:229], s[4:5], 0, v[126:127]
	global_load_lds_dwordx4 v[228:229], off
	s_mov_b32 m0, s17
	v_lshl_add_u64 v[228:229], v[232:233], 0, s[64:65]
	global_load_lds_dwordx4 v[228:229], off
	s_mov_b32 m0, s18
	v_lshl_add_u64 v[228:229], v[244:245], 0, s[64:65]
	global_load_lds_dwordx4 v[228:229], off
	s_waitcnt vmcnt(8) lgkmcnt(0)
	s_setprio 1
	s_barrier
	v_mfma_f32_16x16x32_bf16 v[62:65], v[160:163], v[192:195], v[62:65]
	v_mfma_f32_16x16x32_bf16 v[58:61], v[168:171], v[192:195], v[58:61]
	v_mfma_f32_16x16x32_bf16 v[54:57], v[160:163], v[200:203], v[54:57]
	v_mfma_f32_16x16x32_bf16 v[50:53], v[168:171], v[200:203], v[50:53]
	v_mfma_f32_16x16x32_bf16 v[38:41], v[160:163], v[208:211], v[38:41]
	v_mfma_f32_16x16x32_bf16 v[34:37], v[168:171], v[208:211], v[34:37]
	v_mfma_f32_16x16x32_bf16 v[22:25], v[160:163], v[216:219], v[22:25]
	v_mfma_f32_16x16x32_bf16 v[18:21], v[168:171], v[216:219], v[18:21]
	v_mfma_f32_16x16x32_bf16 v[62:65], v[164:167], v[196:199], v[62:65]
	v_mfma_f32_16x16x32_bf16 v[58:61], v[172:175], v[196:199], v[58:61]
	v_mfma_f32_16x16x32_bf16 v[54:57], v[164:167], v[204:207], v[54:57]
	v_mfma_f32_16x16x32_bf16 v[50:53], v[172:175], v[204:207], v[50:53]
	v_mfma_f32_16x16x32_bf16 v[38:41], v[164:167], v[212:215], v[38:41]
	v_mfma_f32_16x16x32_bf16 v[34:37], v[172:175], v[212:215], v[34:37]
	v_mfma_f32_16x16x32_bf16 v[22:25], v[164:167], v[224:227], v[22:25]
	v_mfma_f32_16x16x32_bf16 v[18:21], v[172:175], v[224:227], v[18:21]
	v_mfma_f32_16x16x32_bf16 v[46:49], v[176:179], v[192:195], v[46:49]
	v_mfma_f32_16x16x32_bf16 v[42:45], v[184:187], v[192:195], v[42:45]
	v_mfma_f32_16x16x32_bf16 v[30:33], v[176:179], v[200:203], v[30:33]
	v_mfma_f32_16x16x32_bf16 v[26:29], v[184:187], v[200:203], v[26:29]
	v_mfma_f32_16x16x32_bf16 v[14:17], v[176:179], v[208:211], v[14:17]
	v_mfma_f32_16x16x32_bf16 v[10:13], v[184:187], v[208:211], v[10:13]
	v_mfma_f32_16x16x32_bf16 v[6:9], v[176:179], v[216:219], v[6:9]
	v_mfma_f32_16x16x32_bf16 v[2:5], v[184:187], v[216:219], v[2:5]
	v_mfma_f32_16x16x32_bf16 v[46:49], v[180:183], v[196:199], v[46:49]
	v_mfma_f32_16x16x32_bf16 v[42:45], v[188:191], v[196:199], v[42:45]
	v_mfma_f32_16x16x32_bf16 v[30:33], v[180:183], v[204:207], v[30:33]
	v_mfma_f32_16x16x32_bf16 v[26:29], v[188:191], v[204:207], v[26:29]
	v_mfma_f32_16x16x32_bf16 v[14:17], v[180:183], v[212:215], v[14:17]
	v_mfma_f32_16x16x32_bf16 v[10:13], v[188:191], v[212:215], v[10:13]
	v_mfma_f32_16x16x32_bf16 v[6:9], v[180:183], v[224:227], v[6:9]
	v_mfma_f32_16x16x32_bf16 v[2:5], v[188:191], v[224:227], v[2:5]
	s_setprio 0
	s_barrier
	s_add_i32 s19, s19, 2
	s_add_u32 s0, s0, 0x100
	s_addc_u32 s1, s1, 0
	s_cmp_gt_u32 s19, 29
	s_cbranch_scc0 .LBB0_307
	s_cmpk_lt_u32 s8, 0x100
	s_cbranch_scc0 .LBB0_310
	s_barrier

; #define PG8_STAGE(bufoff, gbase, voff) do { _Pragma("unroll") for (int _i = 0; _i < 2; ++_i) \
;         __builtin_amdgcn_global_load_lds((const unsigned*)((const char*)(gbase) + (voff)[_i]), (PG8_LAS unsigned*)(lds + (bufoff) + ldsw + _i * 8192), 16, 0, 0); } while (0)
; #define PG8_LDA(dst, b, h) do { _Pragma("unroll") for (int m = 0; m < 4; ++m) _Pragma("unroll") for (int k = 0; k < 2; ++k) dst[m][k] = *(const PG8_LAS bf16x8*)(lds + PG8_SA(b, h) + aoff + m * 2048 + k * 1024); } while (0)
; #define PG8_LDB(dst, b, h) do { _Pragma("unroll") for (int n = 0; n < 2; ++n) _Pragma("unroll") for (int k = 0; k < 2; ++k) dst[n][k] = *(const PG8_LAS bf16x8*)(lds + PG8_SB(b, h) + boff + n * 2048 + k * 1024); } while (0)
; #define PG8_MMA(ai, bj, At, Bt) do { __builtin_amdgcn_s_setprio(1); _Pragma("unroll") for (int m = 0; m < 4; ++m) _Pragma("unroll") for (int n = 0; n < 2; ++n) _Pragma("unroll") for (int k = 0; k < 2; ++k) \
;         acc[ai][bj][m][n] = __builtin_amdgcn_mfma_f32_16x16x32_bf16(Bt[n][k], At[m][k], acc[ai][bj][m][n], 0, 0, 0); __builtin_amdgcn_s_setprio(0); } while (0)
; #define PG8_WAIT_V(n) asm volatile("s_waitcnt vmcnt(" #n ")" ::: "memory")
; #define PG8_WAIT_L(n) asm volatile("s_waitcnt lgkmcnt(" #n ")" ::: "memory")
; template <class Epi, class Sched, bool ALIGN_EPI = false, bool SP2 = false>
; __device__ __forceinline__ void gemm_phase(PG8_LAS unsigned char* lds, const Gemm g, const Sched& S, const Epi& E) {
;     ...
;             const bool last = (t == nt - 2);
;             const char* a1 = cA + (size_t)(t + 1) * kstep;
;             const char* a2 = last ? nA : cA + (size_t)(t + 2) * kstep; const char* b2 = last ? nB : cB + (size_t)(t + 2) * kstep;
;             const char* a3 = a2 + kstep; const char* b3 = b2 + kstep;
;             if (last && has_next) S.a_ready(nxt);
;             if constexpr (SP2) {
;             PG8_LDB(B0, 0, 0); PG8_LDB(B1, 0, 1); PG8_SCHED; PG8_LDA(At, 0, 0); PG8_STAGE(PG8_SA(1, 1), a1 + hstep, voffA);
;             PG8_WAIT_V(8); PG8_WAIT_L(0); PG8_BAR; PG8_MMA(0, 0, At, B0); PG8_MMA(0, 1, At, B1); PG8_BAR; PG8_SCHED;
;             PG8_LDA(At, 0, 1); PG8_STAGE(PG8_SB(0, 0), b2, voffB); PG8_STAGE(PG8_SB(0, 1), b2 + hstep, voffB); PG8_STAGE(PG8_SA(0, 0), a2, voffA);
;             PG8_WAIT_V(8); PG8_WAIT_L(0); PG8_BAR; PG8_MMA(1, 0, At, B0); PG8_MMA(1, 1, At, B1); PG8_BAR; PG8_SCHED;
.LBB0_733:
	s_add_u32 s22, s18, s20
	s_addc_u32 s23, s19, s21
	s_add_u32 s22, s22, 0x100
	s_addc_u32 s23, s23, 0
	s_add_u32 s26, s86, s20
	s_addc_u32 s27, s87, s21
	s_add_i32 s40, 0, 0x10000
	s_cmpk_eq_i32 s20, 0xf00
	s_cselect_b32 s25, s13, s23
	s_cselect_b32 s24, s82, s22
	s_cselect_b32 s23, s9, s27
	s_cselect_b32 s22, s83, s26
	s_add_i32 s41, 0, 0x14000
	v_add_u32_e32 v160, s40, v245
	v_add_u32_e32 v176, s41, v245
	ds_read_b128 v[148:151], v160
	ds_read_b128 v[152:155], v160 offset:1024
	ds_read_b128 v[156:159], v160 offset:2048
	ds_read_b128 v[160:163], v160 offset:3072
	ds_read_b128 v[164:167], v176
	ds_read_b128 v[168:171], v176 offset:1024
	ds_read_b128 v[172:175], v176 offset:2048
	ds_read_b128 v[176:179], v176 offset:3072
	v_lshl_add_u64 v[232:233], v[228:229], 0, s[20:21]
	s_add_i32 m0, s31, 0xc000
	ds_read_b128 v[180:183], v247
	ds_read_b128 v[184:187], v247 offset:1024
	ds_read_b128 v[188:191], v247 offset:2048
	ds_read_b128 v[192:195], v247 offset:3072
	ds_read_b128 v[196:199], v247 offset:4096
	ds_read_b128 v[200:203], v247 offset:5120
	ds_read_b128 v[204:207], v247 offset:6144
	ds_read_b128 v[208:211], v247 offset:7168
	global_load_lds_dwordx4 v[232:233], off
	s_add_i32 m0, s31, 0xe000
	v_lshl_add_u64 v[232:233], v[230:231], 0, s[20:21]
	global_load_lds_dwordx4 v[232:233], off
	s_waitcnt vmcnt(8) lgkmcnt(0)
	s_setprio 1
	s_barrier
	v_mfma_f32_16x16x32_bf16 v[144:147], v[148:151], v[180:183], v[144:147]
	v_mfma_f32_16x16x32_bf16 v[122:125], v[156:159], v[180:183], v[122:125]
	v_mfma_f32_16x16x32_bf16 v[110:113], v[148:151], v[188:191], v[110:113]
	v_mfma_f32_16x16x32_bf16 v[106:109], v[156:159], v[188:191], v[106:109]
	v_mfma_f32_16x16x32_bf16 v[94:97], v[148:151], v[196:199], v[94:97]
	v_mfma_f32_16x16x32_bf16 v[90:93], v[156:159], v[196:199], v[90:93]
	v_mfma_f32_16x16x32_bf16 v[78:81], v[148:151], v[204:207], v[78:81]
	v_mfma_f32_16x16x32_bf16 v[74:77], v[156:159], v[204:207], v[74:77]
	v_mfma_f32_16x16x32_bf16 v[144:147], v[152:155], v[184:187], v[144:147]
	v_mfma_f32_16x16x32_bf16 v[122:125], v[160:163], v[184:187], v[122:125]
	v_mfma_f32_16x16x32_bf16 v[110:113], v[152:155], v[192:195], v[110:113]
	v_mfma_f32_16x16x32_bf16 v[106:109], v[160:163], v[192:195], v[106:109]
	v_mfma_f32_16x16x32_bf16 v[94:97], v[152:155], v[200:203], v[94:97]
	v_mfma_f32_16x16x32_bf16 v[90:93], v[160:163], v[200:203], v[90:93]
	v_mfma_f32_16x16x32_bf16 v[78:81], v[152:155], v[208:211], v[78:81]
	v_mfma_f32_16x16x32_bf16 v[74:77], v[160:163], v[208:211], v[74:77]
	v_mfma_f32_16x16x32_bf16 v[118:121], v[164:167], v[180:183], v[118:121]
	v_mfma_f32_16x16x32_bf16 v[114:117], v[172:175], v[180:183], v[114:117]
	v_mfma_f32_16x16x32_bf16 v[102:105], v[164:167], v[188:191], v[102:105]
	v_mfma_f32_16x16x32_bf16 v[98:101], v[172:175], v[188:191], v[98:101]
	v_mfma_f32_16x16x32_bf16 v[86:89], v[164:167], v[196:199], v[86:89]
	v_mfma_f32_16x16x32_bf16 v[82:85], v[172:175], v[196:199], v[82:85]
	v_mfma_f32_16x16x32_bf16 v[70:73], v[164:167], v[204:207], v[70:73]
	v_mfma_f32_16x16x32_bf16 v[66:69], v[172:175], v[204:207], v[66:69]
	v_mfma_f32_16x16x32_bf16 v[118:121], v[168:171], v[184:187], v[118:121]
	v_mfma_f32_16x16x32_bf16 v[114:117], v[176:179], v[184:187], v[114:117]
	v_mfma_f32_16x16x32_bf16 v[102:105], v[168:171], v[192:195], v[102:105]
	v_mfma_f32_16x16x32_bf16 v[98:101], v[176:179], v[192:195], v[98:101]
	v_mfma_f32_16x16x32_bf16 v[86:89], v[168:171], v[200:203], v[86:89]
	v_mfma_f32_16x16x32_bf16 v[82:85], v[176:179], v[200:203], v[82:85]
	v_mfma_f32_16x16x32_bf16 v[70:73], v[168:171], v[208:211], v[70:73]
	v_mfma_f32_16x16x32_bf16 v[66:69], v[176:179], v[208:211], v[66:69]
	s_setprio 0
	s_barrier
	s_add_i32 s26, s40, s30
	v_lshl_add_u64 v[232:233], s[22:23], 0, v[0:1]
	s_mov_b32 m0, s26
	ds_read_b128 v[180:183], v247 offset:16384
	ds_read_b128 v[184:187], v247 offset:17408
	ds_read_b128 v[188:191], v247 offset:18432
	ds_read_b128 v[192:195], v247 offset:19456
	ds_read_b128 v[196:199], v247 offset:20480
	ds_read_b128 v[200:203], v247 offset:21504
	ds_read_b128 v[204:207], v247 offset:22528
	ds_read_b128 v[208:211], v247 offset:23552
	global_load_lds_dwordx4 v[232:233], off
	s_add_i32 m0, s26, 0x2000
	s_add_u32 s26, s22, 0x80000
	v_lshl_add_u64 v[248:249], s[22:23], 0, v[126:127]
	s_addc_u32 s27, s23, 0
	s_add_i32 s40, s41, s30
	global_load_lds_dwordx4 v[248:249], off
	v_lshl_add_u64 v[250:251], s[26:27], 0, v[0:1]
	s_mov_b32 m0, s40
	v_lshl_add_u64 v[220:221], s[24:25], 0, v[212:213]
	global_load_lds_dwordx4 v[250:251], off
	s_add_i32 m0, s40, 0x2000
	v_lshl_add_u64 v[250:251], s[26:27], 0, v[126:127]
	global_load_lds_dwordx4 v[250:251], off
	s_mov_b32 m0, s31
	v_lshl_add_u64 v[250:251], s[24:25], 0, v[214:215]
	global_load_lds_dwordx4 v[250:251], off
	s_mov_b32 m0, s34
	s_nop 0
	global_load_lds_dwordx4 v[220:221], off
	s_waitcnt vmcnt(8) lgkmcnt(0)
	s_setprio 1
	s_barrier
; #define PG8_STAGE(bufoff, gbase, voff) do { _Pragma("unroll") for (int _i = 0; _i < 2; ++_i) \
;         __builtin_amdgcn_global_load_lds((const unsigned*)((const char*)(gbase) + (voff)[_i]), (PG8_LAS unsigned*)(lds + (bufoff) + ldsw + _i * 8192), 16, 0, 0); } while (0)
; #define PG8_LDA(dst, b, h) do { _Pragma("unroll") for (int m = 0; m < 4; ++m) _Pragma("unroll") for (int k = 0; k < 2; ++k) dst[m][k] = *(const PG8_LAS bf16x8*)(lds + PG8_SA(b, h) + aoff + m * 2048 + k * 1024); } while (0)
; #define PG8_LDB(dst, b, h) do { _Pragma("unroll") for (int n = 0; n < 2; ++n) _Pragma("unroll") for (int k = 0; k < 2; ++k) dst[n][k] = *(const PG8_LAS bf16x8*)(lds + PG8_SB(b, h) + boff + n * 2048 + k * 1024); } while (0)
; #define PG8_MMA(ai, bj, At, Bt) do { __builtin_amdgcn_s_setprio(1); _Pragma("unroll") for (int m = 0; m < 4; ++m) _Pragma("unroll") for (int n = 0; n < 2; ++n) _Pragma("unroll") for (int k = 0; k < 2; ++k) \
;         acc[ai][bj][m][n] = __builtin_amdgcn_mfma_f32_16x16x32_bf16(Bt[n][k], At[m][k], acc[ai][bj][m][n], 0, 0, 0); __builtin_amdgcn_s_setprio(0); } while (0)
; #define PG8_WAIT_V(n) asm volatile("s_waitcnt vmcnt(" #n ")" ::: "memory")
; #define PG8_WAIT_L(n) asm volatile("s_waitcnt lgkmcnt(" #n ")" ::: "memory")
; #define PG8_BAR __builtin_amdgcn_s_barrier()
; #define PG8_SCHED __builtin_amdgcn_sched_barrier(0)
; template <class Epi, class Sched, bool ALIGN_EPI = false, bool SP2 = false>
; __device__ __forceinline__ void gemm_phase(PG8_LAS unsigned char* lds, const Gemm g, const Sched& S, const Epi& E) {
;     ...
;             PG8_WAIT_V(8); PG8_WAIT_L(0); PG8_BAR; PG8_MMA(1, 0, At, B0); PG8_MMA(1, 1, At, B1); PG8_BAR; PG8_SCHED;
;             PG8_LDB(B0, 1, 0); PG8_LDB(B1, 1, 1); PG8_SCHED; PG8_LDA(At, 1, 0); PG8_STAGE(PG8_SA(0, 1), a2 + hstep, voffA);
;             PG8_WAIT_V(8); PG8_WAIT_L(0); PG8_BAR; PG8_MMA(0, 0, At, B0); PG8_MMA(0, 1, At, B1); PG8_BAR; PG8_SCHED;
	v_mfma_f32_16x16x32_bf16 v[62:65], v[148:151], v[180:183], v[62:65]
	v_mfma_f32_16x16x32_bf16 v[58:61], v[156:159], v[180:183], v[58:61]
	v_mfma_f32_16x16x32_bf16 v[46:49], v[148:151], v[188:191], v[46:49]
	v_mfma_f32_16x16x32_bf16 v[42:45], v[156:159], v[188:191], v[42:45]
	v_mfma_f32_16x16x32_bf16 v[30:33], v[148:151], v[196:199], v[30:33]
	v_mfma_f32_16x16x32_bf16 v[26:29], v[156:159], v[196:199], v[26:29]
	v_mfma_f32_16x16x32_bf16 v[14:17], v[148:151], v[204:207], v[14:17]
	v_mfma_f32_16x16x32_bf16 v[10:13], v[156:159], v[204:207], v[10:13]
	v_mfma_f32_16x16x32_bf16 v[62:65], v[152:155], v[184:187], v[62:65]
	v_mfma_f32_16x16x32_bf16 v[58:61], v[160:163], v[184:187], v[58:61]
	v_mfma_f32_16x16x32_bf16 v[46:49], v[152:155], v[192:195], v[46:49]
	v_mfma_f32_16x16x32_bf16 v[42:45], v[160:163], v[192:195], v[42:45]
	v_mfma_f32_16x16x32_bf16 v[30:33], v[152:155], v[200:203], v[30:33]
	v_mfma_f32_16x16x32_bf16 v[26:29], v[160:163], v[200:203], v[26:29]
	v_mfma_f32_16x16x32_bf16 v[14:17], v[152:155], v[208:211], v[14:17]
	v_mfma_f32_16x16x32_bf16 v[10:13], v[160:163], v[208:211], v[10:13]
	v_mfma_f32_16x16x32_bf16 v[54:57], v[164:167], v[180:183], v[54:57]
	v_mfma_f32_16x16x32_bf16 v[50:53], v[172:175], v[180:183], v[50:53]
	v_mfma_f32_16x16x32_bf16 v[38:41], v[164:167], v[188:191], v[38:41]
	v_mfma_f32_16x16x32_bf16 v[34:37], v[172:175], v[188:191], v[34:37]
	v_mfma_f32_16x16x32_bf16 v[22:25], v[164:167], v[196:199], v[22:25]
	v_mfma_f32_16x16x32_bf16 v[18:21], v[172:175], v[196:199], v[18:21]
	v_mfma_f32_16x16x32_bf16 v[6:9], v[164:167], v[204:207], v[6:9]
	v_mfma_f32_16x16x32_bf16 v[2:5], v[172:175], v[204:207], v[2:5]
	v_mfma_f32_16x16x32_bf16 v[54:57], v[168:171], v[184:187], v[54:57]
	v_mfma_f32_16x16x32_bf16 v[50:53], v[176:179], v[184:187], v[50:53]
	v_mfma_f32_16x16x32_bf16 v[38:41], v[168:171], v[192:195], v[38:41]
	v_mfma_f32_16x16x32_bf16 v[34:37], v[176:179], v[192:195], v[34:37]
	v_mfma_f32_16x16x32_bf16 v[22:25], v[168:171], v[200:203], v[22:25]
	v_mfma_f32_16x16x32_bf16 v[18:21], v[176:179], v[200:203], v[18:21]
	v_mfma_f32_16x16x32_bf16 v[6:9], v[168:171], v[208:211], v[6:9]
	v_mfma_f32_16x16x32_bf16 v[2:5], v[176:179], v[208:211], v[2:5]
	s_setprio 0
	s_barrier
	s_add_i32 s26, 0, 0x18000
	s_add_i32 s27, 0, 0x1c000
	v_add_u32_e32 v160, s26, v245
	v_add_u32_e32 v176, s27, v245
	ds_read_b128 v[148:151], v160
	ds_read_b128 v[152:155], v160 offset:1024
	ds_read_b128 v[156:159], v160 offset:2048
	ds_read_b128 v[160:163], v160 offset:3072
	ds_read_b128 v[164:167], v176
	ds_read_b128 v[168:171], v176 offset:1024
	ds_read_b128 v[172:175], v176 offset:2048
	ds_read_b128 v[176:179], v176 offset:3072
	s_add_u32 s24, s24, 0x80000
	s_addc_u32 s25, s25, 0
	s_mov_b32 m0, s35
	v_lshl_add_u64 v[222:223], s[24:25], 0, v[214:215]
	ds_read_b128 v[180:183], v247 offset:32768
	ds_read_b128 v[184:187], v247 offset:33792
	ds_read_b128 v[188:191], v247 offset:34816
	ds_read_b128 v[192:195], v247 offset:35840
	ds_read_b128 v[196:199], v247 offset:36864
	ds_read_b128 v[200:203], v247 offset:37888
	ds_read_b128 v[204:207], v247 offset:38912
	ds_read_b128 v[208:211], v247 offset:39936
	global_load_lds_dwordx4 v[222:223], off
	s_mov_b32 m0, s36
	v_lshl_add_u64 v[222:223], s[24:25], 0, v[212:213]
	global_load_lds_dwordx4 v[222:223], off
	s_waitcnt vmcnt(8) lgkmcnt(0)
	s_setprio 1
	s_barrier
	v_mfma_f32_16x16x32_bf16 v[144:147], v[148:151], v[180:183], v[144:147]
	v_mfma_f32_16x16x32_bf16 v[122:125], v[156:159], v[180:183], v[122:125]
	v_mfma_f32_16x16x32_bf16 v[110:113], v[148:151], v[188:191], v[110:113]
	v_mfma_f32_16x16x32_bf16 v[106:109], v[156:159], v[188:191], v[106:109]
	v_mfma_f32_16x16x32_bf16 v[94:97], v[148:151], v[196:199], v[94:97]
	v_mfma_f32_16x16x32_bf16 v[90:93], v[156:159], v[196:199], v[90:93]
	v_mfma_f32_16x16x32_bf16 v[78:81], v[148:151], v[204:207], v[78:81]
	v_mfma_f32_16x16x32_bf16 v[74:77], v[156:159], v[204:207], v[74:77]
	v_mfma_f32_16x16x32_bf16 v[144:147], v[152:155], v[184:187], v[144:147]
	v_mfma_f32_16x16x32_bf16 v[122:125], v[160:163], v[184:187], v[122:125]
	v_mfma_f32_16x16x32_bf16 v[110:113], v[152:155], v[192:195], v[110:113]
	v_mfma_f32_16x16x32_bf16 v[106:109], v[160:163], v[192:195], v[106:109]
	v_mfma_f32_16x16x32_bf16 v[94:97], v[152:155], v[200:203], v[94:97]
	v_mfma_f32_16x16x32_bf16 v[90:93], v[160:163], v[200:203], v[90:93]
	v_mfma_f32_16x16x32_bf16 v[78:81], v[152:155], v[208:211], v[78:81]
	v_mfma_f32_16x16x32_bf16 v[74:77], v[160:163], v[208:211], v[74:77]
	v_mfma_f32_16x16x32_bf16 v[118:121], v[164:167], v[180:183], v[118:121]
	v_mfma_f32_16x16x32_bf16 v[114:117], v[172:175], v[180:183], v[114:117]
	v_mfma_f32_16x16x32_bf16 v[102:105], v[164:167], v[188:191], v[102:105]
	v_mfma_f32_16x16x32_bf16 v[98:101], v[172:175], v[188:191], v[98:101]
	v_mfma_f32_16x16x32_bf16 v[86:89], v[164:167], v[196:199], v[86:89]
	v_mfma_f32_16x16x32_bf16 v[82:85], v[172:175], v[196:199], v[82:85]
	v_mfma_f32_16x16x32_bf16 v[70:73], v[164:167], v[204:207], v[70:73]
	v_mfma_f32_16x16x32_bf16 v[66:69], v[172:175], v[204:207], v[66:69]
	v_mfma_f32_16x16x32_bf16 v[118:121], v[168:171], v[184:187], v[118:121]
	v_mfma_f32_16x16x32_bf16 v[114:117], v[176:179], v[184:187], v[114:117]
	v_mfma_f32_16x16x32_bf16 v[102:105], v[168:171], v[192:195], v[102:105]
	v_mfma_f32_16x16x32_bf16 v[98:101], v[176:179], v[192:195], v[98:101]
	v_mfma_f32_16x16x32_bf16 v[86:89], v[168:171], v[200:203], v[86:89]
	v_mfma_f32_16x16x32_bf16 v[82:85], v[176:179], v[200:203], v[82:85]
	v_mfma_f32_16x16x32_bf16 v[70:73], v[168:171], v[208:211], v[70:73]
	v_mfma_f32_16x16x32_bf16 v[66:69], v[176:179], v[208:211], v[66:69]
	s_setprio 0
	s_barrier
; #define PG8_STAGE(bufoff, gbase, voff) do { _Pragma("unroll") for (int _i = 0; _i < 2; ++_i) \
;         __builtin_amdgcn_global_load_lds((const unsigned*)((const char*)(gbase) + (voff)[_i]), (PG8_LAS unsigned*)(lds + (bufoff) + ldsw + _i * 8192), 16, 0, 0); } while (0)
; #define PG8_LDA(dst, b, h) do { _Pragma("unroll") for (int m = 0; m < 4; ++m) _Pragma("unroll") for (int k = 0; k < 2; ++k) dst[m][k] = *(const PG8_LAS bf16x8*)(lds + PG8_SA(b, h) + aoff + m * 2048 + k * 1024); } while (0)
; #define PG8_MMA(ai, bj, At, Bt) do { __builtin_amdgcn_s_setprio(1); _Pragma("unroll") for (int m = 0; m < 4; ++m) _Pragma("unroll") for (int n = 0; n < 2; ++n) _Pragma("unroll") for (int k = 0; k < 2; ++k) \
;         acc[ai][bj][m][n] = __builtin_amdgcn_mfma_f32_16x16x32_bf16(Bt[n][k], At[m][k], acc[ai][bj][m][n], 0, 0, 0); __builtin_amdgcn_s_setprio(0); } while (0)
; #define PG8_WAIT_V(n) asm volatile("s_waitcnt vmcnt(" #n ")" ::: "memory")
; #define PG8_WAIT_L(n) asm volatile("s_waitcnt lgkmcnt(" #n ")" ::: "memory")
; #define PG8_BAR __builtin_amdgcn_s_barrier()
; #define PG8_SCHED __builtin_amdgcn_sched_barrier(0)
; template <class Epi, class Sched, bool ALIGN_EPI = false, bool SP2 = false>
; __device__ __forceinline__ void gemm_phase(PG8_LAS unsigned char* lds, const Gemm g, const Sched& S, const Epi& E) {
;     ...
;         for (int t = 0; t < nt; t += 2) {
;     ...
;             PG8_LDA(At, 1, 1); PG8_STAGE(PG8_SB(1, 0), b3, voffB); PG8_STAGE(PG8_SB(1, 1), b3 + hstep, voffB); PG8_STAGE(PG8_SA(1, 0), a3, voffA);
;             PG8_WAIT_V(8); PG8_WAIT_L(0); PG8_BAR; PG8_MMA(1, 0, At, B0); PG8_MMA(1, 1, At, B1); PG8_BAR; PG8_SCHED;
	s_add_i32 s24, s26, s30
	v_lshl_add_u64 v[222:223], v[232:233], 0, s[64:65]
	s_mov_b32 m0, s24
	ds_read_b128 v[180:183], v247 offset:49152
	ds_read_b128 v[184:187], v247 offset:50176
	ds_read_b128 v[188:191], v247 offset:51200
	ds_read_b128 v[192:195], v247 offset:52224
	ds_read_b128 v[196:199], v247 offset:53248
	ds_read_b128 v[200:203], v247 offset:54272
	ds_read_b128 v[204:207], v247 offset:55296
	ds_read_b128 v[208:211], v247 offset:56320
	global_load_lds_dwordx4 v[222:223], off
	s_add_i32 m0, s24, 0x2000
	s_add_u32 s22, s22, 0x80080
	v_lshl_add_u64 v[222:223], v[248:249], 0, s[64:65]
	s_addc_u32 s23, s23, 0
	s_add_i32 s24, s27, s30
	global_load_lds_dwordx4 v[222:223], off
	v_lshl_add_u64 v[222:223], s[22:23], 0, v[0:1]
	s_mov_b32 m0, s24
	v_lshl_add_u64 v[220:221], v[220:221], 0, s[64:65]
	global_load_lds_dwordx4 v[222:223], off
	s_add_i32 m0, s24, 0x2000
	v_lshl_add_u64 v[222:223], s[22:23], 0, v[126:127]
	global_load_lds_dwordx4 v[222:223], off
	s_mov_b32 m0, s37
	v_lshl_add_u64 v[222:223], v[250:251], 0, s[64:65]
	global_load_lds_dwordx4 v[222:223], off
	s_mov_b32 m0, s84
	s_nop 0
	global_load_lds_dwordx4 v[220:221], off
	s_waitcnt vmcnt(8) lgkmcnt(0)
	s_setprio 1
	s_barrier
	v_mfma_f32_16x16x32_bf16 v[62:65], v[148:151], v[180:183], v[62:65]
	v_mfma_f32_16x16x32_bf16 v[58:61], v[156:159], v[180:183], v[58:61]
	v_mfma_f32_16x16x32_bf16 v[46:49], v[148:151], v[188:191], v[46:49]
	v_mfma_f32_16x16x32_bf16 v[42:45], v[156:159], v[188:191], v[42:45]
	v_mfma_f32_16x16x32_bf16 v[30:33], v[148:151], v[196:199], v[30:33]
	v_mfma_f32_16x16x32_bf16 v[26:29], v[156:159], v[196:199], v[26:29]
	v_mfma_f32_16x16x32_bf16 v[14:17], v[148:151], v[204:207], v[14:17]
	v_mfma_f32_16x16x32_bf16 v[10:13], v[156:159], v[204:207], v[10:13]
	v_mfma_f32_16x16x32_bf16 v[62:65], v[152:155], v[184:187], v[62:65]
	v_mfma_f32_16x16x32_bf16 v[58:61], v[160:163], v[184:187], v[58:61]
	v_mfma_f32_16x16x32_bf16 v[46:49], v[152:155], v[192:195], v[46:49]
	v_mfma_f32_16x16x32_bf16 v[42:45], v[160:163], v[192:195], v[42:45]
	v_mfma_f32_16x16x32_bf16 v[30:33], v[152:155], v[200:203], v[30:33]
	v_mfma_f32_16x16x32_bf16 v[26:29], v[160:163], v[200:203], v[26:29]
	v_mfma_f32_16x16x32_bf16 v[14:17], v[152:155], v[208:211], v[14:17]
	v_mfma_f32_16x16x32_bf16 v[10:13], v[160:163], v[208:211], v[10:13]
	v_mfma_f32_16x16x32_bf16 v[54:57], v[164:167], v[180:183], v[54:57]
	v_mfma_f32_16x16x32_bf16 v[50:53], v[172:175], v[180:183], v[50:53]
	v_mfma_f32_16x16x32_bf16 v[38:41], v[164:167], v[188:191], v[38:41]
	v_mfma_f32_16x16x32_bf16 v[34:37], v[172:175], v[188:191], v[34:37]
	v_mfma_f32_16x16x32_bf16 v[22:25], v[164:167], v[196:199], v[22:25]
	v_mfma_f32_16x16x32_bf16 v[18:21], v[172:175], v[196:199], v[18:21]
	v_mfma_f32_16x16x32_bf16 v[6:9], v[164:167], v[204:207], v[6:9]
	v_mfma_f32_16x16x32_bf16 v[2:5], v[172:175], v[204:207], v[2:5]
	v_mfma_f32_16x16x32_bf16 v[54:57], v[168:171], v[184:187], v[54:57]
	v_mfma_f32_16x16x32_bf16 v[50:53], v[176:179], v[184:187], v[50:53]
	v_mfma_f32_16x16x32_bf16 v[38:41], v[168:171], v[192:195], v[38:41]
	v_mfma_f32_16x16x32_bf16 v[34:37], v[176:179], v[192:195], v[34:37]
	v_mfma_f32_16x16x32_bf16 v[22:25], v[168:171], v[200:203], v[22:25]
	v_mfma_f32_16x16x32_bf16 v[18:21], v[176:179], v[200:203], v[18:21]
	v_mfma_f32_16x16x32_bf16 v[6:9], v[168:171], v[208:211], v[6:9]
	v_mfma_f32_16x16x32_bf16 v[2:5], v[176:179], v[208:211], v[2:5]
	s_setprio 0
	s_barrier
	s_add_i32 s22, s76, 2
	s_add_u32 s20, s20, 0x100
	s_addc_u32 s21, s21, 0
	s_cmp_gt_u32 s76, 29
	s_mov_b32 s76, s22
	s_cbranch_scc1 .LBB0_742

; #define PG8_STAGE(bufoff, gbase, voff) do { _Pragma("unroll") for (int _i = 0; _i < 2; ++_i) \
;         __builtin_amdgcn_global_load_lds((const unsigned*)((const char*)(gbase) + (voff)[_i]), (PG8_LAS unsigned*)(lds + (bufoff) + ldsw + _i * 8192), 16, 0, 0); } while (0)
; #define PG8_LDA(dst, b, h) do { _Pragma("unroll") for (int m = 0; m < 4; ++m) _Pragma("unroll") for (int k = 0; k < 2; ++k) dst[m][k] = *(const PG8_LAS bf16x8*)(lds + PG8_SA(b, h) + aoff + m * 2048 + k * 1024); } while (0)
; #define PG8_LDB(dst, b, h) do { _Pragma("unroll") for (int n = 0; n < 2; ++n) _Pragma("unroll") for (int k = 0; k < 2; ++k) dst[n][k] = *(const PG8_LAS bf16x8*)(lds + PG8_SB(b, h) + boff + n * 2048 + k * 1024); } while (0)
; #define PG8_MMA(ai, bj, At, Bt) do { __builtin_amdgcn_s_setprio(1); _Pragma("unroll") for (int m = 0; m < 4; ++m) _Pragma("unroll") for (int n = 0; n < 2; ++n) _Pragma("unroll") for (int k = 0; k < 2; ++k) \
;         acc[ai][bj][m][n] = __builtin_amdgcn_mfma_f32_16x16x32_bf16(Bt[n][k], At[m][k], acc[ai][bj][m][n], 0, 0, 0); __builtin_amdgcn_s_setprio(0); } while (0)
; #define PG8_WAIT_V(n) asm volatile("s_waitcnt vmcnt(" #n ")" ::: "memory")
; #define PG8_WAIT_L(n) asm volatile("s_waitcnt lgkmcnt(" #n ")" ::: "memory")
; template <class Epi, class Sched, bool ALIGN_EPI = false, bool SP2 = false>
; __device__ __forceinline__ void gemm_phase(PG8_LAS unsigned char* lds, const Gemm g, const Sched& S, const Epi& E) {
;     ...
;             const bool last = (t == nt - 2);
;             const char* a1 = cA + (size_t)(t + 1) * kstep;
;             const char* a2 = last ? nA : cA + (size_t)(t + 2) * kstep; const char* b2 = last ? nB : cB + (size_t)(t + 2) * kstep;
;             const char* a3 = a2 + kstep; const char* b3 = b2 + kstep;
;             if (last && has_next) S.a_ready(nxt);
;             if constexpr (SP2) {
;             PG8_LDB(B0, 0, 0); PG8_LDB(B1, 0, 1); PG8_SCHED; PG8_LDA(At, 0, 0); PG8_STAGE(PG8_SA(1, 1), a1 + hstep, voffA);
;             PG8_WAIT_V(8); PG8_WAIT_L(0); PG8_BAR; PG8_MMA(0, 0, At, B0); PG8_MMA(0, 1, At, B1); PG8_BAR; PG8_SCHED;
;             PG8_LDA(At, 0, 1); PG8_STAGE(PG8_SB(0, 0), b2, voffB); PG8_STAGE(PG8_SB(0, 1), b2 + hstep, voffB); PG8_STAGE(PG8_SA(0, 0), a2, voffA);
;             PG8_WAIT_V(8); PG8_WAIT_L(0); PG8_BAR; PG8_MMA(1, 0, At, B0); PG8_MMA(1, 1, At, B1); PG8_BAR; PG8_SCHED;
.LBB0_808:
	s_add_u32 s28, s8, 0xfff80080
	s_addc_u32 s29, s9, -1
	s_add_i32 s48, 0, 0x10000
	s_cmp_eq_u32 s87, 28
	s_cselect_b32 s31, s23, s29
	s_cselect_b32 s30, s67, s28
	v_add_u32_e32 v160, s48, v163
	s_cselect_b32 s29, s21, s86
	s_cselect_b32 s28, s81, s83
	s_add_i32 s91, 0, 0x14000
	ds_read_b128 v[152:155], v160
	ds_read_b128 v[156:159], v160 offset:1024
	ds_read_b128 v[166:169], v160 offset:2048
	ds_read_b128 v[170:173], v160 offset:3072
	v_add_u32_e32 v160, s91, v163
	ds_read_b128 v[174:177], v160
	ds_read_b128 v[178:181], v160 offset:1024
	ds_read_b128 v[182:185], v160 offset:2048
	ds_read_b128 v[186:189], v160 offset:3072
	v_lshl_add_u64 v[160:161], s[8:9], 0, v[148:149]
	s_add_i32 m0, s13, 0xc000
	ds_read_b128 v[190:193], v165
	ds_read_b128 v[194:197], v165 offset:1024
	ds_read_b128 v[198:201], v165 offset:2048
	ds_read_b128 v[202:205], v165 offset:3072
	ds_read_b128 v[206:209], v165 offset:4096
	ds_read_b128 v[210:213], v165 offset:5120
	ds_read_b128 v[214:217], v165 offset:6144
	ds_read_b128 v[224:227], v165 offset:7168
	global_load_lds_dwordx4 v[160:161], off
	s_add_i32 m0, s13, 0xe000
	v_lshl_add_u64 v[160:161], s[8:9], 0, v[150:151]
	global_load_lds_dwordx4 v[160:161], off
	s_waitcnt vmcnt(8) lgkmcnt(0)
	s_setprio 1
	s_barrier
	v_mfma_f32_16x16x32_bf16 v[144:147], v[152:155], v[190:193], v[144:147]
	v_mfma_f32_16x16x32_bf16 v[122:125], v[166:169], v[190:193], v[122:125]
	v_mfma_f32_16x16x32_bf16 v[110:113], v[152:155], v[198:201], v[110:113]
	v_mfma_f32_16x16x32_bf16 v[106:109], v[166:169], v[198:201], v[106:109]
	v_mfma_f32_16x16x32_bf16 v[94:97], v[152:155], v[206:209], v[94:97]
	v_mfma_f32_16x16x32_bf16 v[90:93], v[166:169], v[206:209], v[90:93]
	v_mfma_f32_16x16x32_bf16 v[78:81], v[152:155], v[214:217], v[78:81]
	v_mfma_f32_16x16x32_bf16 v[74:77], v[166:169], v[214:217], v[74:77]
	v_mfma_f32_16x16x32_bf16 v[144:147], v[156:159], v[194:197], v[144:147]
	v_mfma_f32_16x16x32_bf16 v[122:125], v[170:173], v[194:197], v[122:125]
	v_mfma_f32_16x16x32_bf16 v[110:113], v[156:159], v[202:205], v[110:113]
	v_mfma_f32_16x16x32_bf16 v[106:109], v[170:173], v[202:205], v[106:109]
	v_mfma_f32_16x16x32_bf16 v[94:97], v[156:159], v[210:213], v[94:97]
	v_mfma_f32_16x16x32_bf16 v[90:93], v[170:173], v[210:213], v[90:93]
	v_mfma_f32_16x16x32_bf16 v[78:81], v[156:159], v[224:227], v[78:81]
	v_mfma_f32_16x16x32_bf16 v[74:77], v[170:173], v[224:227], v[74:77]
	v_mfma_f32_16x16x32_bf16 v[118:121], v[174:177], v[190:193], v[118:121]
	v_mfma_f32_16x16x32_bf16 v[114:117], v[182:185], v[190:193], v[114:117]
	v_mfma_f32_16x16x32_bf16 v[102:105], v[174:177], v[198:201], v[102:105]
	v_mfma_f32_16x16x32_bf16 v[98:101], v[182:185], v[198:201], v[98:101]
	v_mfma_f32_16x16x32_bf16 v[86:89], v[174:177], v[206:209], v[86:89]
	v_mfma_f32_16x16x32_bf16 v[82:85], v[182:185], v[206:209], v[82:85]
	v_mfma_f32_16x16x32_bf16 v[70:73], v[174:177], v[214:217], v[70:73]
	v_mfma_f32_16x16x32_bf16 v[66:69], v[182:185], v[214:217], v[66:69]
	v_mfma_f32_16x16x32_bf16 v[118:121], v[178:181], v[194:197], v[118:121]
	v_mfma_f32_16x16x32_bf16 v[114:117], v[186:189], v[194:197], v[114:117]
	v_mfma_f32_16x16x32_bf16 v[102:105], v[178:181], v[202:205], v[102:105]
	v_mfma_f32_16x16x32_bf16 v[98:101], v[186:189], v[202:205], v[98:101]
	v_mfma_f32_16x16x32_bf16 v[86:89], v[178:181], v[210:213], v[86:89]
	v_mfma_f32_16x16x32_bf16 v[82:85], v[186:189], v[210:213], v[82:85]
	v_mfma_f32_16x16x32_bf16 v[70:73], v[178:181], v[224:227], v[70:73]
	v_mfma_f32_16x16x32_bf16 v[66:69], v[186:189], v[224:227], v[66:69]
	s_setprio 0
	s_barrier
	s_add_i32 s48, s48, s12
	v_lshl_add_u64 v[160:161], s[28:29], 0, v[0:1]
	s_mov_b32 m0, s48
	ds_read_b128 v[190:193], v165 offset:16384
	ds_read_b128 v[194:197], v165 offset:17408
	ds_read_b128 v[198:201], v165 offset:18432
	ds_read_b128 v[202:205], v165 offset:19456
	ds_read_b128 v[206:209], v165 offset:20480
	ds_read_b128 v[210:213], v165 offset:21504
	ds_read_b128 v[214:217], v165 offset:22528
	ds_read_b128 v[224:227], v165 offset:23552
	global_load_lds_dwordx4 v[160:161], off
	s_add_i32 m0, s48, 0x2000
	s_add_u32 vcc_lo, s28, 0x80000
	v_lshl_add_u64 v[218:219], s[28:29], 0, v[126:127]
	s_addc_u32 vcc_hi, s29, 0
	s_add_i32 s48, s91, s12
	global_load_lds_dwordx4 v[218:219], off
	v_lshl_add_u64 v[220:221], vcc, 0, v[0:1]
	s_mov_b32 m0, s48
	v_lshl_add_u64 v[222:223], s[30:31], 0, v[126:127]
	global_load_lds_dwordx4 v[220:221], off
	s_add_i32 m0, s48, 0x2000
	v_lshl_add_u64 v[220:221], vcc, 0, v[126:127]
	global_load_lds_dwordx4 v[220:221], off
	s_mov_b32 m0, s13
	v_lshl_add_u64 v[220:221], s[30:31], 0, v[0:1]
	global_load_lds_dwordx4 v[220:221], off
	s_mov_b32 m0, s34
	s_nop 0
	global_load_lds_dwordx4 v[222:223], off
	s_waitcnt vmcnt(8) lgkmcnt(0)
	s_setprio 1
	s_barrier
; #define PG8_STAGE(bufoff, gbase, voff) do { _Pragma("unroll") for (int _i = 0; _i < 2; ++_i) \
;         __builtin_amdgcn_global_load_lds((const unsigned*)((const char*)(gbase) + (voff)[_i]), (PG8_LAS unsigned*)(lds + (bufoff) + ldsw + _i * 8192), 16, 0, 0); } while (0)
; #define PG8_LDA(dst, b, h) do { _Pragma("unroll") for (int m = 0; m < 4; ++m) _Pragma("unroll") for (int k = 0; k < 2; ++k) dst[m][k] = *(const PG8_LAS bf16x8*)(lds + PG8_SA(b, h) + aoff + m * 2048 + k * 1024); } while (0)
; #define PG8_LDB(dst, b, h) do { _Pragma("unroll") for (int n = 0; n < 2; ++n) _Pragma("unroll") for (int k = 0; k < 2; ++k) dst[n][k] = *(const PG8_LAS bf16x8*)(lds + PG8_SB(b, h) + boff + n * 2048 + k * 1024); } while (0)
; #define PG8_MMA(ai, bj, At, Bt) do { __builtin_amdgcn_s_setprio(1); _Pragma("unroll") for (int m = 0; m < 4; ++m) _Pragma("unroll") for (int n = 0; n < 2; ++n) _Pragma("unroll") for (int k = 0; k < 2; ++k) \
;         acc[ai][bj][m][n] = __builtin_amdgcn_mfma_f32_16x16x32_bf16(Bt[n][k], At[m][k], acc[ai][bj][m][n], 0, 0, 0); __builtin_amdgcn_s_setprio(0); } while (0)
; #define PG8_WAIT_V(n) asm volatile("s_waitcnt vmcnt(" #n ")" ::: "memory")
; #define PG8_WAIT_L(n) asm volatile("s_waitcnt lgkmcnt(" #n ")" ::: "memory")
; #define PG8_BAR __builtin_amdgcn_s_barrier()
; #define PG8_SCHED __builtin_amdgcn_sched_barrier(0)
; template <class Epi, class Sched, bool ALIGN_EPI = false, bool SP2 = false>
; __device__ __forceinline__ void gemm_phase(PG8_LAS unsigned char* lds, const Gemm g, const Sched& S, const Epi& E) {
;     ...
;             PG8_WAIT_V(8); PG8_WAIT_L(0); PG8_BAR; PG8_MMA(1, 0, At, B0); PG8_MMA(1, 1, At, B1); PG8_BAR; PG8_SCHED;
;             PG8_LDB(B0, 1, 0); PG8_LDB(B1, 1, 1); PG8_SCHED; PG8_LDA(At, 1, 0); PG8_STAGE(PG8_SA(0, 1), a2 + hstep, voffA);
;             PG8_WAIT_V(8); PG8_WAIT_L(0); PG8_BAR; PG8_MMA(0, 0, At, B0); PG8_MMA(0, 1, At, B1); PG8_BAR; PG8_SCHED;
	v_mfma_f32_16x16x32_bf16 v[62:65], v[152:155], v[190:193], v[62:65]
	v_mfma_f32_16x16x32_bf16 v[58:61], v[166:169], v[190:193], v[58:61]
	v_mfma_f32_16x16x32_bf16 v[46:49], v[152:155], v[198:201], v[46:49]
	v_mfma_f32_16x16x32_bf16 v[42:45], v[166:169], v[198:201], v[42:45]
	v_mfma_f32_16x16x32_bf16 v[30:33], v[152:155], v[206:209], v[30:33]
	v_mfma_f32_16x16x32_bf16 v[26:29], v[166:169], v[206:209], v[26:29]
	v_mfma_f32_16x16x32_bf16 v[14:17], v[152:155], v[214:217], v[14:17]
	v_mfma_f32_16x16x32_bf16 v[10:13], v[166:169], v[214:217], v[10:13]
	v_mfma_f32_16x16x32_bf16 v[62:65], v[156:159], v[194:197], v[62:65]
	v_mfma_f32_16x16x32_bf16 v[58:61], v[170:173], v[194:197], v[58:61]
	v_mfma_f32_16x16x32_bf16 v[46:49], v[156:159], v[202:205], v[46:49]
	v_mfma_f32_16x16x32_bf16 v[42:45], v[170:173], v[202:205], v[42:45]
	v_mfma_f32_16x16x32_bf16 v[30:33], v[156:159], v[210:213], v[30:33]
	v_mfma_f32_16x16x32_bf16 v[26:29], v[170:173], v[210:213], v[26:29]
	v_mfma_f32_16x16x32_bf16 v[14:17], v[156:159], v[224:227], v[14:17]
	v_mfma_f32_16x16x32_bf16 v[10:13], v[170:173], v[224:227], v[10:13]
	v_mfma_f32_16x16x32_bf16 v[54:57], v[174:177], v[190:193], v[54:57]
	v_mfma_f32_16x16x32_bf16 v[50:53], v[182:185], v[190:193], v[50:53]
	v_mfma_f32_16x16x32_bf16 v[38:41], v[174:177], v[198:201], v[38:41]
	v_mfma_f32_16x16x32_bf16 v[34:37], v[182:185], v[198:201], v[34:37]
	v_mfma_f32_16x16x32_bf16 v[22:25], v[174:177], v[206:209], v[22:25]
	v_mfma_f32_16x16x32_bf16 v[18:21], v[182:185], v[206:209], v[18:21]
	v_mfma_f32_16x16x32_bf16 v[6:9], v[174:177], v[214:217], v[6:9]
	v_mfma_f32_16x16x32_bf16 v[2:5], v[182:185], v[214:217], v[2:5]
	v_mfma_f32_16x16x32_bf16 v[54:57], v[178:181], v[194:197], v[54:57]
	v_mfma_f32_16x16x32_bf16 v[50:53], v[186:189], v[194:197], v[50:53]
	v_mfma_f32_16x16x32_bf16 v[38:41], v[178:181], v[202:205], v[38:41]
	v_mfma_f32_16x16x32_bf16 v[34:37], v[186:189], v[202:205], v[34:37]
	v_mfma_f32_16x16x32_bf16 v[22:25], v[178:181], v[210:213], v[22:25]
	v_mfma_f32_16x16x32_bf16 v[18:21], v[186:189], v[210:213], v[18:21]
	v_mfma_f32_16x16x32_bf16 v[6:9], v[178:181], v[224:227], v[6:9]
	v_mfma_f32_16x16x32_bf16 v[2:5], v[186:189], v[224:227], v[2:5]
	s_setprio 0
	s_barrier
	s_add_i32 s48, 0, 0x18000
	s_add_i32 s91, 0, 0x1c000
	v_add_u32_e32 v170, s48, v163
	v_add_u32_e32 v186, s91, v163
	ds_read_b128 v[152:155], v170
	ds_read_b128 v[156:159], v170 offset:1024
	ds_read_b128 v[166:169], v170 offset:2048
	ds_read_b128 v[170:173], v170 offset:3072
	ds_read_b128 v[174:177], v186
	ds_read_b128 v[178:181], v186 offset:1024
	ds_read_b128 v[182:185], v186 offset:2048
	ds_read_b128 v[186:189], v186 offset:3072
	s_add_u32 s30, s30, 0x80000
	s_addc_u32 s31, s31, 0
	s_mov_b32 m0, s35
	v_lshl_add_u64 v[228:229], s[30:31], 0, v[0:1]
	ds_read_b128 v[190:193], v165 offset:32768
	ds_read_b128 v[194:197], v165 offset:33792
	ds_read_b128 v[198:201], v165 offset:34816
	ds_read_b128 v[202:205], v165 offset:35840
	ds_read_b128 v[206:209], v165 offset:36864
	ds_read_b128 v[210:213], v165 offset:37888
	ds_read_b128 v[214:217], v165 offset:38912
	ds_read_b128 v[224:227], v165 offset:39936
	global_load_lds_dwordx4 v[228:229], off
	s_mov_b32 m0, s42
	v_lshl_add_u64 v[228:229], s[30:31], 0, v[126:127]
	global_load_lds_dwordx4 v[228:229], off
	s_waitcnt vmcnt(8) lgkmcnt(0)
	s_setprio 1
	s_barrier
	v_mfma_f32_16x16x32_bf16 v[144:147], v[152:155], v[190:193], v[144:147]
	v_mfma_f32_16x16x32_bf16 v[122:125], v[166:169], v[190:193], v[122:125]
	v_mfma_f32_16x16x32_bf16 v[110:113], v[152:155], v[198:201], v[110:113]
	v_mfma_f32_16x16x32_bf16 v[106:109], v[166:169], v[198:201], v[106:109]
	v_mfma_f32_16x16x32_bf16 v[94:97], v[152:155], v[206:209], v[94:97]
	v_mfma_f32_16x16x32_bf16 v[90:93], v[166:169], v[206:209], v[90:93]
	v_mfma_f32_16x16x32_bf16 v[78:81], v[152:155], v[214:217], v[78:81]
	v_mfma_f32_16x16x32_bf16 v[74:77], v[166:169], v[214:217], v[74:77]
	v_mfma_f32_16x16x32_bf16 v[144:147], v[156:159], v[194:197], v[144:147]
	v_mfma_f32_16x16x32_bf16 v[122:125], v[170:173], v[194:197], v[122:125]
	v_mfma_f32_16x16x32_bf16 v[110:113], v[156:159], v[202:205], v[110:113]
	v_mfma_f32_16x16x32_bf16 v[106:109], v[170:173], v[202:205], v[106:109]
	v_mfma_f32_16x16x32_bf16 v[94:97], v[156:159], v[210:213], v[94:97]
	v_mfma_f32_16x16x32_bf16 v[90:93], v[170:173], v[210:213], v[90:93]
	v_mfma_f32_16x16x32_bf16 v[78:81], v[156:159], v[224:227], v[78:81]
	v_mfma_f32_16x16x32_bf16 v[74:77], v[170:173], v[224:227], v[74:77]
	v_mfma_f32_16x16x32_bf16 v[118:121], v[174:177], v[190:193], v[118:121]
	v_mfma_f32_16x16x32_bf16 v[114:117], v[182:185], v[190:193], v[114:117]
	v_mfma_f32_16x16x32_bf16 v[102:105], v[174:177], v[198:201], v[102:105]
	v_mfma_f32_16x16x32_bf16 v[98:101], v[182:185], v[198:201], v[98:101]
	v_mfma_f32_16x16x32_bf16 v[86:89], v[174:177], v[206:209], v[86:89]
	v_mfma_f32_16x16x32_bf16 v[82:85], v[182:185], v[206:209], v[82:85]
	v_mfma_f32_16x16x32_bf16 v[70:73], v[174:177], v[214:217], v[70:73]
	v_mfma_f32_16x16x32_bf16 v[66:69], v[182:185], v[214:217], v[66:69]
	v_mfma_f32_16x16x32_bf16 v[118:121], v[178:181], v[194:197], v[118:121]
	v_mfma_f32_16x16x32_bf16 v[114:117], v[186:189], v[194:197], v[114:117]
	v_mfma_f32_16x16x32_bf16 v[102:105], v[178:181], v[202:205], v[102:105]
	v_mfma_f32_16x16x32_bf16 v[98:101], v[186:189], v[202:205], v[98:101]
	v_mfma_f32_16x16x32_bf16 v[86:89], v[178:181], v[210:213], v[86:89]
	v_mfma_f32_16x16x32_bf16 v[82:85], v[186:189], v[210:213], v[82:85]
	v_mfma_f32_16x16x32_bf16 v[70:73], v[178:181], v[224:227], v[70:73]
	v_mfma_f32_16x16x32_bf16 v[66:69], v[186:189], v[224:227], v[66:69]
	s_setprio 0
	s_barrier
; #define PG8_STAGE(bufoff, gbase, voff) do { _Pragma("unroll") for (int _i = 0; _i < 2; ++_i) \
;         __builtin_amdgcn_global_load_lds((const unsigned*)((const char*)(gbase) + (voff)[_i]), (PG8_LAS unsigned*)(lds + (bufoff) + ldsw + _i * 8192), 16, 0, 0); } while (0)
; #define PG8_LDA(dst, b, h) do { _Pragma("unroll") for (int m = 0; m < 4; ++m) _Pragma("unroll") for (int k = 0; k < 2; ++k) dst[m][k] = *(const PG8_LAS bf16x8*)(lds + PG8_SA(b, h) + aoff + m * 2048 + k * 1024); } while (0)
; #define PG8_MMA(ai, bj, At, Bt) do { __builtin_amdgcn_s_setprio(1); _Pragma("unroll") for (int m = 0; m < 4; ++m) _Pragma("unroll") for (int n = 0; n < 2; ++n) _Pragma("unroll") for (int k = 0; k < 2; ++k) \
;         acc[ai][bj][m][n] = __builtin_amdgcn_mfma_f32_16x16x32_bf16(Bt[n][k], At[m][k], acc[ai][bj][m][n], 0, 0, 0); __builtin_amdgcn_s_setprio(0); } while (0)
; #define PG8_WAIT_V(n) asm volatile("s_waitcnt vmcnt(" #n ")" ::: "memory")
; #define PG8_WAIT_L(n) asm volatile("s_waitcnt lgkmcnt(" #n ")" ::: "memory")
; #define PG8_BAR __builtin_amdgcn_s_barrier()
; #define PG8_SCHED __builtin_amdgcn_sched_barrier(0)
; template <class Epi, class Sched, bool ALIGN_EPI = false, bool SP2 = false>
; __device__ __forceinline__ void gemm_phase(PG8_LAS unsigned char* lds, const Gemm g, const Sched& S, const Epi& E) {
;     ...
;             PG8_LDA(At, 1, 1); PG8_STAGE(PG8_SB(1, 0), b3, voffB); PG8_STAGE(PG8_SB(1, 1), b3 + hstep, voffB); PG8_STAGE(PG8_SA(1, 0), a3, voffA);
;             PG8_WAIT_V(8); PG8_WAIT_L(0); PG8_BAR; PG8_MMA(1, 0, At, B0); PG8_MMA(1, 1, At, B1); PG8_BAR; PG8_SCHED;
;     ...
;         if constexpr (ALIGN_EPI) { if (wr == 0) PG8_BAR; }
	s_add_i32 s30, s48, s12
	v_lshl_add_u64 v[160:161], v[160:161], 0, s[64:65]
	s_mov_b32 m0, s30
	ds_read_b128 v[190:193], v165 offset:49152
	ds_read_b128 v[194:197], v165 offset:50176
	ds_read_b128 v[198:201], v165 offset:51200
	ds_read_b128 v[202:205], v165 offset:52224
	ds_read_b128 v[206:209], v165 offset:53248
	ds_read_b128 v[210:213], v165 offset:54272
	ds_read_b128 v[214:217], v165 offset:55296
	ds_read_b128 v[224:227], v165 offset:56320
	global_load_lds_dwordx4 v[160:161], off
	s_add_i32 m0, s30, 0x2000
	s_add_u32 s28, s28, 0x80080
	v_lshl_add_u64 v[160:161], v[218:219], 0, s[64:65]
	s_addc_u32 s29, s29, 0
	s_add_i32 s30, s91, s12
	global_load_lds_dwordx4 v[160:161], off
	s_mov_b32 m0, s30
	v_lshl_add_u64 v[160:161], s[28:29], 0, v[0:1]
	global_load_lds_dwordx4 v[160:161], off
	s_add_i32 m0, s30, 0x2000
	v_lshl_add_u64 v[160:161], s[28:29], 0, v[126:127]
	global_load_lds_dwordx4 v[160:161], off
	s_mov_b32 m0, s43
	v_lshl_add_u64 v[160:161], v[220:221], 0, s[64:65]
	global_load_lds_dwordx4 v[160:161], off
	s_mov_b32 m0, s76
	v_lshl_add_u64 v[160:161], v[222:223], 0, s[64:65]
	global_load_lds_dwordx4 v[160:161], off
	s_waitcnt vmcnt(8) lgkmcnt(0)
	s_setprio 1
	s_barrier
	v_mfma_f32_16x16x32_bf16 v[62:65], v[152:155], v[190:193], v[62:65]
	v_mfma_f32_16x16x32_bf16 v[58:61], v[166:169], v[190:193], v[58:61]
	v_mfma_f32_16x16x32_bf16 v[46:49], v[152:155], v[198:201], v[46:49]
	v_mfma_f32_16x16x32_bf16 v[42:45], v[166:169], v[198:201], v[42:45]
	v_mfma_f32_16x16x32_bf16 v[30:33], v[152:155], v[206:209], v[30:33]
	v_mfma_f32_16x16x32_bf16 v[26:29], v[166:169], v[206:209], v[26:29]
	v_mfma_f32_16x16x32_bf16 v[14:17], v[152:155], v[214:217], v[14:17]
	v_mfma_f32_16x16x32_bf16 v[10:13], v[166:169], v[214:217], v[10:13]
	v_mfma_f32_16x16x32_bf16 v[62:65], v[156:159], v[194:197], v[62:65]
	v_mfma_f32_16x16x32_bf16 v[58:61], v[170:173], v[194:197], v[58:61]
	v_mfma_f32_16x16x32_bf16 v[46:49], v[156:159], v[202:205], v[46:49]
	v_mfma_f32_16x16x32_bf16 v[42:45], v[170:173], v[202:205], v[42:45]
	v_mfma_f32_16x16x32_bf16 v[30:33], v[156:159], v[210:213], v[30:33]
	v_mfma_f32_16x16x32_bf16 v[26:29], v[170:173], v[210:213], v[26:29]
	v_mfma_f32_16x16x32_bf16 v[14:17], v[156:159], v[224:227], v[14:17]
	v_mfma_f32_16x16x32_bf16 v[10:13], v[170:173], v[224:227], v[10:13]
	v_mfma_f32_16x16x32_bf16 v[54:57], v[174:177], v[190:193], v[54:57]
	v_mfma_f32_16x16x32_bf16 v[50:53], v[182:185], v[190:193], v[50:53]
	v_mfma_f32_16x16x32_bf16 v[38:41], v[174:177], v[198:201], v[38:41]
	v_mfma_f32_16x16x32_bf16 v[34:37], v[182:185], v[198:201], v[34:37]
	v_mfma_f32_16x16x32_bf16 v[22:25], v[174:177], v[206:209], v[22:25]
	v_mfma_f32_16x16x32_bf16 v[18:21], v[182:185], v[206:209], v[18:21]
	v_mfma_f32_16x16x32_bf16 v[6:9], v[174:177], v[214:217], v[6:9]
	v_mfma_f32_16x16x32_bf16 v[2:5], v[182:185], v[214:217], v[2:5]
	v_mfma_f32_16x16x32_bf16 v[54:57], v[178:181], v[194:197], v[54:57]
	v_mfma_f32_16x16x32_bf16 v[50:53], v[186:189], v[194:197], v[50:53]
	v_mfma_f32_16x16x32_bf16 v[38:41], v[178:181], v[202:205], v[38:41]
	v_mfma_f32_16x16x32_bf16 v[34:37], v[186:189], v[202:205], v[34:37]
	v_mfma_f32_16x16x32_bf16 v[22:25], v[178:181], v[210:213], v[22:25]
	v_mfma_f32_16x16x32_bf16 v[18:21], v[186:189], v[210:213], v[18:21]
	v_mfma_f32_16x16x32_bf16 v[6:9], v[178:181], v[224:227], v[6:9]
	v_mfma_f32_16x16x32_bf16 v[2:5], v[186:189], v[224:227], v[2:5]
	s_setprio 0
	s_barrier
	s_add_i32 s87, s87, 2
	s_add_u32 s8, s8, 0x100
	s_addc_u32 s9, s9, 0
	s_add_u32 s83, s83, 0x100
	s_addc_u32 s86, s86, 0
	s_cmp_gt_u32 s87, 29
	s_cbranch_scc0 .LBB0_808
	s_and_b64 vcc, exec, s[18:19]
	s_cbranch_vccz .LBB0_811
	s_barrier

; #define PG8_STAGE(bufoff, gbase, voff) do { _Pragma("unroll") for (int _i = 0; _i < 2; ++_i) \
;         __builtin_amdgcn_global_load_lds((const unsigned*)((const char*)(gbase) + (voff)[_i]), (PG8_LAS unsigned*)(lds + (bufoff) + ldsw + _i * 8192), 16, 0, 0); } while (0)
; #define PG8_LDA(dst, b, h) do { _Pragma("unroll") for (int m = 0; m < 4; ++m) _Pragma("unroll") for (int k = 0; k < 2; ++k) dst[m][k] = *(const PG8_LAS bf16x8*)(lds + PG8_SA(b, h) + aoff + m * 2048 + k * 1024); } while (0)
; #define PG8_LDB(dst, b, h) do { _Pragma("unroll") for (int n = 0; n < 2; ++n) _Pragma("unroll") for (int k = 0; k < 2; ++k) dst[n][k] = *(const PG8_LAS bf16x8*)(lds + PG8_SB(b, h) + boff + n * 2048 + k * 1024); } while (0)
; #define PG8_MMA(ai, bj, At, Bt) do { __builtin_amdgcn_s_setprio(1); _Pragma("unroll") for (int m = 0; m < 4; ++m) _Pragma("unroll") for (int n = 0; n < 2; ++n) _Pragma("unroll") for (int k = 0; k < 2; ++k) \
;         acc[ai][bj][m][n] = __builtin_amdgcn_mfma_f32_16x16x32_bf16(Bt[n][k], At[m][k], acc[ai][bj][m][n], 0, 0, 0); __builtin_amdgcn_s_setprio(0); } while (0)
; #define PG8_WAIT_V(n) asm volatile("s_waitcnt vmcnt(" #n ")" ::: "memory")
; #define PG8_WAIT_L(n) asm volatile("s_waitcnt lgkmcnt(" #n ")" ::: "memory")
; template <class Epi, class Sched, bool ALIGN_EPI = false, bool SP2 = false>
; __device__ __forceinline__ void gemm_phase(PG8_LAS unsigned char* lds, const Gemm g, const Sched& S, const Epi& E) {
;     ...
;             const bool last = (t == nt - 2);
;             const char* a1 = cA + (size_t)(t + 1) * kstep;
;             const char* a2 = last ? nA : cA + (size_t)(t + 2) * kstep; const char* b2 = last ? nB : cB + (size_t)(t + 2) * kstep;
;             const char* a3 = a2 + kstep; const char* b3 = b2 + kstep;
;             if (last && has_next) S.a_ready(nxt);
;             if constexpr (SP2) {
;             PG8_LDB(B0, 0, 0); PG8_LDB(B1, 0, 1); PG8_SCHED; PG8_LDA(At, 0, 0); PG8_STAGE(PG8_SA(1, 1), a1 + hstep, voffA);
;             PG8_WAIT_V(8); PG8_WAIT_L(0); PG8_BAR; PG8_MMA(0, 0, At, B0); PG8_MMA(0, 1, At, B1); PG8_BAR; PG8_SCHED;
;             PG8_LDA(At, 0, 1); PG8_STAGE(PG8_SB(0, 0), b2, voffB); PG8_STAGE(PG8_SB(0, 1), b2 + hstep, voffB); PG8_STAGE(PG8_SA(0, 0), a2, voffA);
;             PG8_WAIT_V(8); PG8_WAIT_L(0); PG8_BAR; PG8_MMA(1, 0, At, B0); PG8_MMA(1, 1, At, B1); PG8_BAR; PG8_SCHED;
.LBB0_910:
	s_add_u32 s28, s0, 0xfff80080
	s_addc_u32 s29, s1, -1
	s_add_i32 s48, 0, 0x10000
	s_cmp_eq_u32 s81, 28
	s_cselect_b32 s31, s21, s29
	s_cselect_b32 s30, s35, s28
	s_cselect_b32 s29, s23, s67
	s_cselect_b32 s28, s40, s41
	s_add_i32 s91, 0, 0x14000
	v_add_u32_e32 v164, s48, v179
	v_add_u32_e32 v176, s91, v179
	ds_read_b128 v[152:155], v164
	ds_read_b128 v[156:159], v164 offset:1024
	ds_read_b128 v[160:163], v164 offset:2048
	ds_read_b128 v[164:167], v164 offset:3072
	ds_read_b128 v[168:171], v176
	ds_read_b128 v[172:175], v176 offset:1024
	ds_read_b128 v[182:185], v176 offset:2048
	ds_read_b128 v[186:189], v176 offset:3072
	v_lshl_add_u64 v[176:177], s[0:1], 0, v[148:149]
	s_add_i32 m0, s43, 0xc000
	ds_read_b128 v[190:193], v181
	ds_read_b128 v[194:197], v181 offset:1024
	ds_read_b128 v[198:201], v181 offset:2048
	ds_read_b128 v[202:205], v181 offset:3072
	ds_read_b128 v[206:209], v181 offset:4096
	ds_read_b128 v[210:213], v181 offset:5120
	ds_read_b128 v[214:217], v181 offset:6144
	ds_read_b128 v[224:227], v181 offset:7168
	global_load_lds_dwordx4 v[176:177], off
	s_add_i32 m0, s43, 0xe000
	v_lshl_add_u64 v[176:177], s[0:1], 0, v[150:151]
	global_load_lds_dwordx4 v[176:177], off
	s_waitcnt vmcnt(8) lgkmcnt(0)
	s_setprio 1
	s_barrier
	v_mfma_f32_16x16x32_bf16 v[74:77], v[152:155], v[190:193], v[74:77]
	v_mfma_f32_16x16x32_bf16 v[78:81], v[160:163], v[190:193], v[78:81]
	v_mfma_f32_16x16x32_bf16 v[102:105], v[152:155], v[198:201], v[102:105]
	v_mfma_f32_16x16x32_bf16 v[106:109], v[160:163], v[198:201], v[106:109]
	v_mfma_f32_16x16x32_bf16 v[122:125], v[152:155], v[206:209], v[122:125]
	v_mfma_f32_16x16x32_bf16 v[144:147], v[160:163], v[206:209], v[144:147]
	v_mfma_f32_16x16x32_bf16 v[90:93], v[152:155], v[214:217], v[90:93]
	v_mfma_f32_16x16x32_bf16 v[86:89], v[160:163], v[214:217], v[86:89]
	v_mfma_f32_16x16x32_bf16 v[74:77], v[156:159], v[194:197], v[74:77]
	v_mfma_f32_16x16x32_bf16 v[78:81], v[164:167], v[194:197], v[78:81]
	v_mfma_f32_16x16x32_bf16 v[102:105], v[156:159], v[202:205], v[102:105]
	v_mfma_f32_16x16x32_bf16 v[106:109], v[164:167], v[202:205], v[106:109]
	v_mfma_f32_16x16x32_bf16 v[122:125], v[156:159], v[210:213], v[122:125]
	v_mfma_f32_16x16x32_bf16 v[144:147], v[164:167], v[210:213], v[144:147]
	v_mfma_f32_16x16x32_bf16 v[90:93], v[156:159], v[224:227], v[90:93]
	v_mfma_f32_16x16x32_bf16 v[86:89], v[164:167], v[224:227], v[86:89]
	v_mfma_f32_16x16x32_bf16 v[82:85], v[168:171], v[190:193], v[82:85]
	v_mfma_f32_16x16x32_bf16 v[94:97], v[182:185], v[190:193], v[94:97]
	v_mfma_f32_16x16x32_bf16 v[110:113], v[168:171], v[198:201], v[110:113]
	v_mfma_f32_16x16x32_bf16 v[118:121], v[182:185], v[198:201], v[118:121]
	v_mfma_f32_16x16x32_bf16 v[114:117], v[168:171], v[206:209], v[114:117]
	v_mfma_f32_16x16x32_bf16 v[98:101], v[182:185], v[206:209], v[98:101]
	v_mfma_f32_16x16x32_bf16 v[70:73], v[168:171], v[214:217], v[70:73]
	v_mfma_f32_16x16x32_bf16 v[66:69], v[182:185], v[214:217], v[66:69]
	v_mfma_f32_16x16x32_bf16 v[82:85], v[172:175], v[194:197], v[82:85]
	v_mfma_f32_16x16x32_bf16 v[94:97], v[186:189], v[194:197], v[94:97]
	v_mfma_f32_16x16x32_bf16 v[110:113], v[172:175], v[202:205], v[110:113]
	v_mfma_f32_16x16x32_bf16 v[118:121], v[186:189], v[202:205], v[118:121]
	v_mfma_f32_16x16x32_bf16 v[114:117], v[172:175], v[210:213], v[114:117]
	v_mfma_f32_16x16x32_bf16 v[98:101], v[186:189], v[210:213], v[98:101]
	v_mfma_f32_16x16x32_bf16 v[70:73], v[172:175], v[224:227], v[70:73]
	v_mfma_f32_16x16x32_bf16 v[66:69], v[186:189], v[224:227], v[66:69]
	s_setprio 0
	s_barrier
	s_add_i32 s48, s48, s42
	v_lshl_add_u64 v[176:177], s[28:29], 0, v[0:1]
	s_mov_b32 m0, s48
	ds_read_b128 v[190:193], v181 offset:16384
	ds_read_b128 v[194:197], v181 offset:17408
	ds_read_b128 v[198:201], v181 offset:18432
	ds_read_b128 v[202:205], v181 offset:19456
	ds_read_b128 v[206:209], v181 offset:20480
	ds_read_b128 v[210:213], v181 offset:21504
	ds_read_b128 v[214:217], v181 offset:22528
	ds_read_b128 v[224:227], v181 offset:23552
	global_load_lds_dwordx4 v[176:177], off
	s_add_i32 m0, s48, 0x2000
	s_add_u32 vcc_lo, s28, 0x80000
	v_lshl_add_u64 v[218:219], s[28:29], 0, v[126:127]
	s_addc_u32 vcc_hi, s29, 0
	s_add_i32 s48, s91, s42
	global_load_lds_dwordx4 v[218:219], off
	v_lshl_add_u64 v[220:221], vcc, 0, v[0:1]
	s_mov_b32 m0, s48
	v_lshl_add_u64 v[222:223], s[30:31], 0, v[126:127]
	global_load_lds_dwordx4 v[220:221], off
	s_add_i32 m0, s48, 0x2000
	v_lshl_add_u64 v[220:221], vcc, 0, v[126:127]
	global_load_lds_dwordx4 v[220:221], off
	s_mov_b32 m0, s43
	v_lshl_add_u64 v[220:221], s[30:31], 0, v[0:1]
	global_load_lds_dwordx4 v[220:221], off
	s_mov_b32 m0, s76
	s_nop 0
	global_load_lds_dwordx4 v[222:223], off
	s_waitcnt vmcnt(8) lgkmcnt(0)
	s_setprio 1
	s_barrier
; #define PG8_STAGE(bufoff, gbase, voff) do { _Pragma("unroll") for (int _i = 0; _i < 2; ++_i) \
;         __builtin_amdgcn_global_load_lds((const unsigned*)((const char*)(gbase) + (voff)[_i]), (PG8_LAS unsigned*)(lds + (bufoff) + ldsw + _i * 8192), 16, 0, 0); } while (0)
; #define PG8_LDA(dst, b, h) do { _Pragma("unroll") for (int m = 0; m < 4; ++m) _Pragma("unroll") for (int k = 0; k < 2; ++k) dst[m][k] = *(const PG8_LAS bf16x8*)(lds + PG8_SA(b, h) + aoff + m * 2048 + k * 1024); } while (0)
; #define PG8_LDB(dst, b, h) do { _Pragma("unroll") for (int n = 0; n < 2; ++n) _Pragma("unroll") for (int k = 0; k < 2; ++k) dst[n][k] = *(const PG8_LAS bf16x8*)(lds + PG8_SB(b, h) + boff + n * 2048 + k * 1024); } while (0)
; #define PG8_MMA(ai, bj, At, Bt) do { __builtin_amdgcn_s_setprio(1); _Pragma("unroll") for (int m = 0; m < 4; ++m) _Pragma("unroll") for (int n = 0; n < 2; ++n) _Pragma("unroll") for (int k = 0; k < 2; ++k) \
;         acc[ai][bj][m][n] = __builtin_amdgcn_mfma_f32_16x16x32_bf16(Bt[n][k], At[m][k], acc[ai][bj][m][n], 0, 0, 0); __builtin_amdgcn_s_setprio(0); } while (0)
; #define PG8_WAIT_V(n) asm volatile("s_waitcnt vmcnt(" #n ")" ::: "memory")
; #define PG8_WAIT_L(n) asm volatile("s_waitcnt lgkmcnt(" #n ")" ::: "memory")
; #define PG8_BAR __builtin_amdgcn_s_barrier()
; #define PG8_SCHED __builtin_amdgcn_sched_barrier(0)
; template <class Epi, class Sched, bool ALIGN_EPI = false, bool SP2 = false>
; __device__ __forceinline__ void gemm_phase(PG8_LAS unsigned char* lds, const Gemm g, const Sched& S, const Epi& E) {
;     ...
;             PG8_WAIT_V(8); PG8_WAIT_L(0); PG8_BAR; PG8_MMA(1, 0, At, B0); PG8_MMA(1, 1, At, B1); PG8_BAR; PG8_SCHED;
;             PG8_LDB(B0, 1, 0); PG8_LDB(B1, 1, 1); PG8_SCHED; PG8_LDA(At, 1, 0); PG8_STAGE(PG8_SA(0, 1), a2 + hstep, voffA);
;             PG8_WAIT_V(8); PG8_WAIT_L(0); PG8_BAR; PG8_MMA(0, 0, At, B0); PG8_MMA(0, 1, At, B1); PG8_BAR; PG8_SCHED;
	v_mfma_f32_16x16x32_bf16 v[62:65], v[152:155], v[190:193], v[62:65]
	v_mfma_f32_16x16x32_bf16 v[58:61], v[160:163], v[190:193], v[58:61]
	v_mfma_f32_16x16x32_bf16 v[46:49], v[152:155], v[198:201], v[46:49]
	v_mfma_f32_16x16x32_bf16 v[42:45], v[160:163], v[198:201], v[42:45]
	v_mfma_f32_16x16x32_bf16 v[30:33], v[152:155], v[206:209], v[30:33]
	v_mfma_f32_16x16x32_bf16 v[26:29], v[160:163], v[206:209], v[26:29]
	v_mfma_f32_16x16x32_bf16 v[14:17], v[152:155], v[214:217], v[14:17]
	v_mfma_f32_16x16x32_bf16 v[10:13], v[160:163], v[214:217], v[10:13]
	v_mfma_f32_16x16x32_bf16 v[62:65], v[156:159], v[194:197], v[62:65]
	v_mfma_f32_16x16x32_bf16 v[58:61], v[164:167], v[194:197], v[58:61]
	v_mfma_f32_16x16x32_bf16 v[46:49], v[156:159], v[202:205], v[46:49]
	v_mfma_f32_16x16x32_bf16 v[42:45], v[164:167], v[202:205], v[42:45]
	v_mfma_f32_16x16x32_bf16 v[30:33], v[156:159], v[210:213], v[30:33]
	v_mfma_f32_16x16x32_bf16 v[26:29], v[164:167], v[210:213], v[26:29]
	v_mfma_f32_16x16x32_bf16 v[14:17], v[156:159], v[224:227], v[14:17]
	v_mfma_f32_16x16x32_bf16 v[10:13], v[164:167], v[224:227], v[10:13]
	v_mfma_f32_16x16x32_bf16 v[54:57], v[168:171], v[190:193], v[54:57]
	v_mfma_f32_16x16x32_bf16 v[50:53], v[182:185], v[190:193], v[50:53]
	v_mfma_f32_16x16x32_bf16 v[38:41], v[168:171], v[198:201], v[38:41]
	v_mfma_f32_16x16x32_bf16 v[34:37], v[182:185], v[198:201], v[34:37]
	v_mfma_f32_16x16x32_bf16 v[22:25], v[168:171], v[206:209], v[22:25]
	v_mfma_f32_16x16x32_bf16 v[18:21], v[182:185], v[206:209], v[18:21]
	v_mfma_f32_16x16x32_bf16 v[6:9], v[168:171], v[214:217], v[6:9]
	v_mfma_f32_16x16x32_bf16 v[2:5], v[182:185], v[214:217], v[2:5]
	v_mfma_f32_16x16x32_bf16 v[54:57], v[172:175], v[194:197], v[54:57]
	v_mfma_f32_16x16x32_bf16 v[50:53], v[186:189], v[194:197], v[50:53]
	v_mfma_f32_16x16x32_bf16 v[38:41], v[172:175], v[202:205], v[38:41]
	v_mfma_f32_16x16x32_bf16 v[34:37], v[186:189], v[202:205], v[34:37]
	v_mfma_f32_16x16x32_bf16 v[22:25], v[172:175], v[210:213], v[22:25]
	v_mfma_f32_16x16x32_bf16 v[18:21], v[186:189], v[210:213], v[18:21]
	v_mfma_f32_16x16x32_bf16 v[6:9], v[172:175], v[224:227], v[6:9]
	v_mfma_f32_16x16x32_bf16 v[2:5], v[186:189], v[224:227], v[2:5]
	s_setprio 0
	s_barrier
	s_add_i32 s48, 0, 0x18000
	s_add_i32 s91, 0, 0x1c000
	v_add_u32_e32 v164, s48, v179
	v_add_u32_e32 v186, s91, v179
	ds_read_b128 v[152:155], v164
	ds_read_b128 v[156:159], v164 offset:1024
	ds_read_b128 v[160:163], v164 offset:2048
	ds_read_b128 v[164:167], v164 offset:3072
	ds_read_b128 v[168:171], v186
	ds_read_b128 v[172:175], v186 offset:1024
	ds_read_b128 v[182:185], v186 offset:2048
	ds_read_b128 v[186:189], v186 offset:3072
	s_add_u32 s30, s30, 0x80000
	s_addc_u32 s31, s31, 0
	s_mov_b32 m0, s82
	v_lshl_add_u64 v[228:229], s[30:31], 0, v[0:1]
	ds_read_b128 v[190:193], v181 offset:32768
	ds_read_b128 v[194:197], v181 offset:33792
	ds_read_b128 v[198:201], v181 offset:34816
	ds_read_b128 v[202:205], v181 offset:35840
	ds_read_b128 v[206:209], v181 offset:36864
	ds_read_b128 v[210:213], v181 offset:37888
	ds_read_b128 v[214:217], v181 offset:38912
	ds_read_b128 v[224:227], v181 offset:39936
	global_load_lds_dwordx4 v[228:229], off
	s_mov_b32 m0, s83
	v_lshl_add_u64 v[228:229], s[30:31], 0, v[126:127]
	global_load_lds_dwordx4 v[228:229], off
	s_waitcnt vmcnt(8) lgkmcnt(0)
	s_setprio 1
	s_barrier
	v_mfma_f32_16x16x32_bf16 v[74:77], v[152:155], v[190:193], v[74:77]
	v_mfma_f32_16x16x32_bf16 v[78:81], v[160:163], v[190:193], v[78:81]
	v_mfma_f32_16x16x32_bf16 v[102:105], v[152:155], v[198:201], v[102:105]
	v_mfma_f32_16x16x32_bf16 v[106:109], v[160:163], v[198:201], v[106:109]
	v_mfma_f32_16x16x32_bf16 v[122:125], v[152:155], v[206:209], v[122:125]
	v_mfma_f32_16x16x32_bf16 v[144:147], v[160:163], v[206:209], v[144:147]
	v_mfma_f32_16x16x32_bf16 v[90:93], v[152:155], v[214:217], v[90:93]
	v_mfma_f32_16x16x32_bf16 v[86:89], v[160:163], v[214:217], v[86:89]
	v_mfma_f32_16x16x32_bf16 v[74:77], v[156:159], v[194:197], v[74:77]
	v_mfma_f32_16x16x32_bf16 v[78:81], v[164:167], v[194:197], v[78:81]
	v_mfma_f32_16x16x32_bf16 v[102:105], v[156:159], v[202:205], v[102:105]
	v_mfma_f32_16x16x32_bf16 v[106:109], v[164:167], v[202:205], v[106:109]
	v_mfma_f32_16x16x32_bf16 v[122:125], v[156:159], v[210:213], v[122:125]
	v_mfma_f32_16x16x32_bf16 v[144:147], v[164:167], v[210:213], v[144:147]
	v_mfma_f32_16x16x32_bf16 v[90:93], v[156:159], v[224:227], v[90:93]
	v_mfma_f32_16x16x32_bf16 v[86:89], v[164:167], v[224:227], v[86:89]
	v_mfma_f32_16x16x32_bf16 v[82:85], v[168:171], v[190:193], v[82:85]
	v_mfma_f32_16x16x32_bf16 v[94:97], v[182:185], v[190:193], v[94:97]
	v_mfma_f32_16x16x32_bf16 v[110:113], v[168:171], v[198:201], v[110:113]
	v_mfma_f32_16x16x32_bf16 v[118:121], v[182:185], v[198:201], v[118:121]
	v_mfma_f32_16x16x32_bf16 v[114:117], v[168:171], v[206:209], v[114:117]
	v_mfma_f32_16x16x32_bf16 v[98:101], v[182:185], v[206:209], v[98:101]
	v_mfma_f32_16x16x32_bf16 v[70:73], v[168:171], v[214:217], v[70:73]
	v_mfma_f32_16x16x32_bf16 v[66:69], v[182:185], v[214:217], v[66:69]
	v_mfma_f32_16x16x32_bf16 v[82:85], v[172:175], v[194:197], v[82:85]
	v_mfma_f32_16x16x32_bf16 v[94:97], v[186:189], v[194:197], v[94:97]
	v_mfma_f32_16x16x32_bf16 v[110:113], v[172:175], v[202:205], v[110:113]
	v_mfma_f32_16x16x32_bf16 v[118:121], v[186:189], v[202:205], v[118:121]
	v_mfma_f32_16x16x32_bf16 v[114:117], v[172:175], v[210:213], v[114:117]
	v_mfma_f32_16x16x32_bf16 v[98:101], v[186:189], v[210:213], v[98:101]
	v_mfma_f32_16x16x32_bf16 v[70:73], v[172:175], v[224:227], v[70:73]
	v_mfma_f32_16x16x32_bf16 v[66:69], v[186:189], v[224:227], v[66:69]
	s_setprio 0
	s_barrier
; #define PG8_STAGE(bufoff, gbase, voff) do { _Pragma("unroll") for (int _i = 0; _i < 2; ++_i) \
;         __builtin_amdgcn_global_load_lds((const unsigned*)((const char*)(gbase) + (voff)[_i]), (PG8_LAS unsigned*)(lds + (bufoff) + ldsw + _i * 8192), 16, 0, 0); } while (0)
; #define PG8_LDA(dst, b, h) do { _Pragma("unroll") for (int m = 0; m < 4; ++m) _Pragma("unroll") for (int k = 0; k < 2; ++k) dst[m][k] = *(const PG8_LAS bf16x8*)(lds + PG8_SA(b, h) + aoff + m * 2048 + k * 1024); } while (0)
; #define PG8_MMA(ai, bj, At, Bt) do { __builtin_amdgcn_s_setprio(1); _Pragma("unroll") for (int m = 0; m < 4; ++m) _Pragma("unroll") for (int n = 0; n < 2; ++n) _Pragma("unroll") for (int k = 0; k < 2; ++k) \
;         acc[ai][bj][m][n] = __builtin_amdgcn_mfma_f32_16x16x32_bf16(Bt[n][k], At[m][k], acc[ai][bj][m][n], 0, 0, 0); __builtin_amdgcn_s_setprio(0); } while (0)
; #define PG8_WAIT_V(n) asm volatile("s_waitcnt vmcnt(" #n ")" ::: "memory")
; #define PG8_WAIT_L(n) asm volatile("s_waitcnt lgkmcnt(" #n ")" ::: "memory")
; #define PG8_BAR __builtin_amdgcn_s_barrier()
; #define PG8_SCHED __builtin_amdgcn_sched_barrier(0)
; template <class Epi, class Sched, bool ALIGN_EPI = false, bool SP2 = false>
; __device__ __forceinline__ void gemm_phase(PG8_LAS unsigned char* lds, const Gemm g, const Sched& S, const Epi& E) {
;     ...
;             PG8_LDA(At, 1, 1); PG8_STAGE(PG8_SB(1, 0), b3, voffB); PG8_STAGE(PG8_SB(1, 1), b3 + hstep, voffB); PG8_STAGE(PG8_SA(1, 0), a3, voffA);
;             PG8_WAIT_V(8); PG8_WAIT_L(0); PG8_BAR; PG8_MMA(1, 0, At, B0); PG8_MMA(1, 1, At, B1); PG8_BAR; PG8_SCHED;
;     ...
;         if constexpr (ALIGN_EPI) { if (wr == 0) PG8_BAR; }
	s_add_i32 s30, s48, s42
	v_lshl_add_u64 v[176:177], v[176:177], 0, s[64:65]
	s_mov_b32 m0, s30
	ds_read_b128 v[190:193], v181 offset:49152
	ds_read_b128 v[194:197], v181 offset:50176
	ds_read_b128 v[198:201], v181 offset:51200
	ds_read_b128 v[202:205], v181 offset:52224
	ds_read_b128 v[206:209], v181 offset:53248
	ds_read_b128 v[210:213], v181 offset:54272
	ds_read_b128 v[214:217], v181 offset:55296
	ds_read_b128 v[224:227], v181 offset:56320
	global_load_lds_dwordx4 v[176:177], off
	s_add_i32 m0, s30, 0x2000
	s_add_u32 s28, s28, 0x80080
	v_lshl_add_u64 v[176:177], v[218:219], 0, s[64:65]
	s_addc_u32 s29, s29, 0
	s_add_i32 s30, s91, s42
	global_load_lds_dwordx4 v[176:177], off
	s_mov_b32 m0, s30
	v_lshl_add_u64 v[176:177], s[28:29], 0, v[0:1]
	global_load_lds_dwordx4 v[176:177], off
	s_add_i32 m0, s30, 0x2000
	v_lshl_add_u64 v[176:177], s[28:29], 0, v[126:127]
	global_load_lds_dwordx4 v[176:177], off
	s_mov_b32 m0, s86
	v_lshl_add_u64 v[176:177], v[220:221], 0, s[64:65]
	global_load_lds_dwordx4 v[176:177], off
	s_mov_b32 m0, s87
	v_lshl_add_u64 v[176:177], v[222:223], 0, s[64:65]
	global_load_lds_dwordx4 v[176:177], off
	s_waitcnt vmcnt(8) lgkmcnt(0)
	s_setprio 1
	s_barrier
	v_mfma_f32_16x16x32_bf16 v[62:65], v[152:155], v[190:193], v[62:65]
	v_mfma_f32_16x16x32_bf16 v[58:61], v[160:163], v[190:193], v[58:61]
	v_mfma_f32_16x16x32_bf16 v[46:49], v[152:155], v[198:201], v[46:49]
	v_mfma_f32_16x16x32_bf16 v[42:45], v[160:163], v[198:201], v[42:45]
	v_mfma_f32_16x16x32_bf16 v[30:33], v[152:155], v[206:209], v[30:33]
	v_mfma_f32_16x16x32_bf16 v[26:29], v[160:163], v[206:209], v[26:29]
	v_mfma_f32_16x16x32_bf16 v[14:17], v[152:155], v[214:217], v[14:17]
	v_mfma_f32_16x16x32_bf16 v[10:13], v[160:163], v[214:217], v[10:13]
	v_mfma_f32_16x16x32_bf16 v[62:65], v[156:159], v[194:197], v[62:65]
	v_mfma_f32_16x16x32_bf16 v[58:61], v[164:167], v[194:197], v[58:61]
	v_mfma_f32_16x16x32_bf16 v[46:49], v[156:159], v[202:205], v[46:49]
	v_mfma_f32_16x16x32_bf16 v[42:45], v[164:167], v[202:205], v[42:45]
	v_mfma_f32_16x16x32_bf16 v[30:33], v[156:159], v[210:213], v[30:33]
	v_mfma_f32_16x16x32_bf16 v[26:29], v[164:167], v[210:213], v[26:29]
	v_mfma_f32_16x16x32_bf16 v[14:17], v[156:159], v[224:227], v[14:17]
	v_mfma_f32_16x16x32_bf16 v[10:13], v[164:167], v[224:227], v[10:13]
	v_mfma_f32_16x16x32_bf16 v[54:57], v[168:171], v[190:193], v[54:57]
	v_mfma_f32_16x16x32_bf16 v[50:53], v[182:185], v[190:193], v[50:53]
	v_mfma_f32_16x16x32_bf16 v[38:41], v[168:171], v[198:201], v[38:41]
	v_mfma_f32_16x16x32_bf16 v[34:37], v[182:185], v[198:201], v[34:37]
	v_mfma_f32_16x16x32_bf16 v[22:25], v[168:171], v[206:209], v[22:25]
	v_mfma_f32_16x16x32_bf16 v[18:21], v[182:185], v[206:209], v[18:21]
	v_mfma_f32_16x16x32_bf16 v[6:9], v[168:171], v[214:217], v[6:9]
	v_mfma_f32_16x16x32_bf16 v[2:5], v[182:185], v[214:217], v[2:5]
	v_mfma_f32_16x16x32_bf16 v[54:57], v[172:175], v[194:197], v[54:57]
	v_mfma_f32_16x16x32_bf16 v[50:53], v[186:189], v[194:197], v[50:53]
	v_mfma_f32_16x16x32_bf16 v[38:41], v[172:175], v[202:205], v[38:41]
	v_mfma_f32_16x16x32_bf16 v[34:37], v[186:189], v[202:205], v[34:37]
	v_mfma_f32_16x16x32_bf16 v[22:25], v[172:175], v[210:213], v[22:25]
	v_mfma_f32_16x16x32_bf16 v[18:21], v[186:189], v[210:213], v[18:21]
	v_mfma_f32_16x16x32_bf16 v[6:9], v[172:175], v[224:227], v[6:9]
	v_mfma_f32_16x16x32_bf16 v[2:5], v[186:189], v[224:227], v[2:5]
	s_setprio 0
	s_barrier
	s_add_i32 s81, s81, 2
	s_add_u32 s0, s0, 0x100
	s_addc_u32 s1, s1, 0
	s_add_u32 s41, s41, 0x100
	s_addc_u32 s67, s67, 0
	s_cmp_gt_u32 s81, 29
	s_cbranch_scc0 .LBB0_910
	s_and_b64 vcc, exec, s[18:19]
	s_cbranch_vccz .LBB0_913
	s_barrier

; #define PG8_STAGE(bufoff, gbase, voff) do { _Pragma("unroll") for (int _i = 0; _i < 2; ++_i) \
;         __builtin_amdgcn_global_load_lds((const unsigned*)((const char*)(gbase) + (voff)[_i]), (PG8_LAS unsigned*)(lds + (bufoff) + ldsw + _i * 8192), 16, 0, 0); } while (0)
; #define PG8_LDA(dst, b, h) do { _Pragma("unroll") for (int m = 0; m < 4; ++m) _Pragma("unroll") for (int k = 0; k < 2; ++k) dst[m][k] = *(const PG8_LAS bf16x8*)(lds + PG8_SA(b, h) + aoff + m * 2048 + k * 1024); } while (0)
; #define PG8_LDB(dst, b, h) do { _Pragma("unroll") for (int n = 0; n < 2; ++n) _Pragma("unroll") for (int k = 0; k < 2; ++k) dst[n][k] = *(const PG8_LAS bf16x8*)(lds + PG8_SB(b, h) + boff + n * 2048 + k * 1024); } while (0)
; #define PG8_MMA(ai, bj, At, Bt) do { __builtin_amdgcn_s_setprio(1); _Pragma("unroll") for (int m = 0; m < 4; ++m) _Pragma("unroll") for (int n = 0; n < 2; ++n) _Pragma("unroll") for (int k = 0; k < 2; ++k) \
;         acc[ai][bj][m][n] = __builtin_amdgcn_mfma_f32_16x16x32_bf16(Bt[n][k], At[m][k], acc[ai][bj][m][n], 0, 0, 0); __builtin_amdgcn_s_setprio(0); } while (0)
; #define PG8_WAIT_V(n) asm volatile("s_waitcnt vmcnt(" #n ")" ::: "memory")
; #define PG8_WAIT_L(n) asm volatile("s_waitcnt lgkmcnt(" #n ")" ::: "memory")
; template <class Epi, class Sched, bool ALIGN_EPI = false, bool SP2 = false>
; __device__ __forceinline__ void gemm_phase(PG8_LAS unsigned char* lds, const Gemm g, const Sched& S, const Epi& E) {
;     ...
;             const bool last = (t == nt - 2);
;             const char* a1 = cA + (size_t)(t + 1) * kstep;
;             const char* a2 = last ? nA : cA + (size_t)(t + 2) * kstep; const char* b2 = last ? nB : cB + (size_t)(t + 2) * kstep;
;             const char* a3 = a2 + kstep; const char* b3 = b2 + kstep;
;             if (last && has_next) S.a_ready(nxt);
;             if constexpr (SP2) {
;             PG8_LDB(B0, 0, 0); PG8_LDB(B1, 0, 1); PG8_SCHED; PG8_LDA(At, 0, 0); PG8_STAGE(PG8_SA(1, 1), a1 + hstep, voffA);
;             PG8_WAIT_V(8); PG8_WAIT_L(0); PG8_BAR; PG8_MMA(0, 0, At, B0); PG8_MMA(0, 1, At, B1); PG8_BAR; PG8_SCHED;
;             PG8_LDA(At, 0, 1); PG8_STAGE(PG8_SB(0, 0), b2, voffB); PG8_STAGE(PG8_SB(0, 1), b2 + hstep, voffB); PG8_STAGE(PG8_SA(0, 0), a2, voffA);
;             PG8_WAIT_V(8); PG8_WAIT_L(0); PG8_BAR; PG8_MMA(1, 0, At, B0); PG8_MMA(1, 1, At, B1); PG8_BAR; PG8_SCHED;
.LBB0_963:
	s_add_u32 s24, s0, 0xfff80080
	s_addc_u32 s25, s1, -1
	s_add_i32 s43, 0, 0x10000
	s_cmp_eq_u32 s42, 28
	s_cselect_b32 s27, s13, s25
	s_cselect_b32 s26, s17, s24
	s_cselect_b32 s25, s19, s41
	s_cselect_b32 s24, s29, s40
	s_add_i32 s48, 0, 0x14000
	v_add_u32_e32 v164, s43, v197
	v_add_u32_e32 v180, s48, v197
	ds_read_b128 v[152:155], v164
	ds_read_b128 v[156:159], v164 offset:1024
	ds_read_b128 v[160:163], v164 offset:2048
	ds_read_b128 v[164:167], v164 offset:3072
	ds_read_b128 v[168:171], v180
	ds_read_b128 v[172:175], v180 offset:1024
	ds_read_b128 v[176:179], v180 offset:2048
	ds_read_b128 v[180:183], v180 offset:3072
	v_lshl_add_u64 v[220:221], s[0:1], 0, v[148:149]
	s_add_i32 m0, s31, 0xc000
	ds_read_b128 v[184:187], v199
	ds_read_b128 v[188:191], v199 offset:1024
	ds_read_b128 v[192:195], v199 offset:2048
	ds_read_b128 v[200:203], v199 offset:3072
	ds_read_b128 v[204:207], v199 offset:4096
	ds_read_b128 v[208:211], v199 offset:5120
	ds_read_b128 v[212:215], v199 offset:6144
	ds_read_b128 v[216:219], v199 offset:7168
	global_load_lds_dwordx4 v[220:221], off
	s_add_i32 m0, s31, 0xe000
	v_lshl_add_u64 v[220:221], s[0:1], 0, v[150:151]
	global_load_lds_dwordx4 v[220:221], off
	s_waitcnt vmcnt(8) lgkmcnt(0)
	s_setprio 1
	s_barrier
	v_mfma_f32_16x16x32_bf16 v[144:147], v[152:155], v[184:187], v[144:147]
	v_mfma_f32_16x16x32_bf16 v[122:125], v[160:163], v[184:187], v[122:125]
	v_mfma_f32_16x16x32_bf16 v[110:113], v[152:155], v[192:195], v[110:113]
	v_mfma_f32_16x16x32_bf16 v[106:109], v[160:163], v[192:195], v[106:109]
	v_mfma_f32_16x16x32_bf16 v[94:97], v[152:155], v[204:207], v[94:97]
	v_mfma_f32_16x16x32_bf16 v[90:93], v[160:163], v[204:207], v[90:93]
	v_mfma_f32_16x16x32_bf16 v[78:81], v[152:155], v[212:215], v[78:81]
	v_mfma_f32_16x16x32_bf16 v[74:77], v[160:163], v[212:215], v[74:77]
	v_mfma_f32_16x16x32_bf16 v[144:147], v[156:159], v[188:191], v[144:147]
	v_mfma_f32_16x16x32_bf16 v[122:125], v[164:167], v[188:191], v[122:125]
	v_mfma_f32_16x16x32_bf16 v[110:113], v[156:159], v[200:203], v[110:113]
	v_mfma_f32_16x16x32_bf16 v[106:109], v[164:167], v[200:203], v[106:109]
	v_mfma_f32_16x16x32_bf16 v[94:97], v[156:159], v[208:211], v[94:97]
	v_mfma_f32_16x16x32_bf16 v[90:93], v[164:167], v[208:211], v[90:93]
	v_mfma_f32_16x16x32_bf16 v[78:81], v[156:159], v[216:219], v[78:81]
	v_mfma_f32_16x16x32_bf16 v[74:77], v[164:167], v[216:219], v[74:77]
	v_mfma_f32_16x16x32_bf16 v[118:121], v[168:171], v[184:187], v[118:121]
	v_mfma_f32_16x16x32_bf16 v[114:117], v[176:179], v[184:187], v[114:117]
	v_mfma_f32_16x16x32_bf16 v[102:105], v[168:171], v[192:195], v[102:105]
	v_mfma_f32_16x16x32_bf16 v[98:101], v[176:179], v[192:195], v[98:101]
	v_mfma_f32_16x16x32_bf16 v[86:89], v[168:171], v[204:207], v[86:89]
	v_mfma_f32_16x16x32_bf16 v[82:85], v[176:179], v[204:207], v[82:85]
	v_mfma_f32_16x16x32_bf16 v[70:73], v[168:171], v[212:215], v[70:73]
	v_mfma_f32_16x16x32_bf16 v[66:69], v[176:179], v[212:215], v[66:69]
	v_mfma_f32_16x16x32_bf16 v[118:121], v[172:175], v[188:191], v[118:121]
	v_mfma_f32_16x16x32_bf16 v[114:117], v[180:183], v[188:191], v[114:117]
	v_mfma_f32_16x16x32_bf16 v[102:105], v[172:175], v[200:203], v[102:105]
	v_mfma_f32_16x16x32_bf16 v[98:101], v[180:183], v[200:203], v[98:101]
	v_mfma_f32_16x16x32_bf16 v[86:89], v[172:175], v[208:211], v[86:89]
	v_mfma_f32_16x16x32_bf16 v[82:85], v[180:183], v[208:211], v[82:85]
	v_mfma_f32_16x16x32_bf16 v[70:73], v[172:175], v[216:219], v[70:73]
	v_mfma_f32_16x16x32_bf16 v[66:69], v[180:183], v[216:219], v[66:69]
	s_setprio 0
	s_barrier
	s_add_i32 s43, s43, s30
	v_lshl_add_u64 v[220:221], s[24:25], 0, v[0:1]
	s_mov_b32 m0, s43
	ds_read_b128 v[184:187], v199 offset:16384
	ds_read_b128 v[188:191], v199 offset:17408
	ds_read_b128 v[192:195], v199 offset:18432
	ds_read_b128 v[200:203], v199 offset:19456
	ds_read_b128 v[204:207], v199 offset:20480
	ds_read_b128 v[208:211], v199 offset:21504
	ds_read_b128 v[212:215], v199 offset:22528
	ds_read_b128 v[216:219], v199 offset:23552
	global_load_lds_dwordx4 v[220:221], off
	s_add_i32 m0, s43, 0x2000
	s_add_u32 vcc_lo, s24, 0x80000
	v_lshl_add_u64 v[222:223], s[24:25], 0, v[126:127]
	s_addc_u32 vcc_hi, s25, 0
	s_add_i32 s43, s48, s30
	global_load_lds_dwordx4 v[222:223], off
	v_lshl_add_u64 v[224:225], vcc, 0, v[0:1]
	s_mov_b32 m0, s43
	v_lshl_add_u64 v[226:227], s[26:27], 0, v[126:127]
	global_load_lds_dwordx4 v[224:225], off
	s_add_i32 m0, s43, 0x2000
	v_lshl_add_u64 v[224:225], vcc, 0, v[126:127]
	global_load_lds_dwordx4 v[224:225], off
	s_mov_b32 m0, s31
	v_lshl_add_u64 v[224:225], s[26:27], 0, v[0:1]
	global_load_lds_dwordx4 v[224:225], off
	s_mov_b32 m0, s34
	s_nop 0
	global_load_lds_dwordx4 v[226:227], off
	s_waitcnt vmcnt(8) lgkmcnt(0)
	s_setprio 1
	s_barrier
; #define PG8_STAGE(bufoff, gbase, voff) do { _Pragma("unroll") for (int _i = 0; _i < 2; ++_i) \
;         __builtin_amdgcn_global_load_lds((const unsigned*)((const char*)(gbase) + (voff)[_i]), (PG8_LAS unsigned*)(lds + (bufoff) + ldsw + _i * 8192), 16, 0, 0); } while (0)
; #define PG8_LDA(dst, b, h) do { _Pragma("unroll") for (int m = 0; m < 4; ++m) _Pragma("unroll") for (int k = 0; k < 2; ++k) dst[m][k] = *(const PG8_LAS bf16x8*)(lds + PG8_SA(b, h) + aoff + m * 2048 + k * 1024); } while (0)
; #define PG8_LDB(dst, b, h) do { _Pragma("unroll") for (int n = 0; n < 2; ++n) _Pragma("unroll") for (int k = 0; k < 2; ++k) dst[n][k] = *(const PG8_LAS bf16x8*)(lds + PG8_SB(b, h) + boff + n * 2048 + k * 1024); } while (0)
; #define PG8_MMA(ai, bj, At, Bt) do { __builtin_amdgcn_s_setprio(1); _Pragma("unroll") for (int m = 0; m < 4; ++m) _Pragma("unroll") for (int n = 0; n < 2; ++n) _Pragma("unroll") for (int k = 0; k < 2; ++k) \
;         acc[ai][bj][m][n] = __builtin_amdgcn_mfma_f32_16x16x32_bf16(Bt[n][k], At[m][k], acc[ai][bj][m][n], 0, 0, 0); __builtin_amdgcn_s_setprio(0); } while (0)
; #define PG8_WAIT_V(n) asm volatile("s_waitcnt vmcnt(" #n ")" ::: "memory")
; #define PG8_WAIT_L(n) asm volatile("s_waitcnt lgkmcnt(" #n ")" ::: "memory")
; #define PG8_BAR __builtin_amdgcn_s_barrier()
; #define PG8_SCHED __builtin_amdgcn_sched_barrier(0)
; template <class Epi, class Sched, bool ALIGN_EPI = false, bool SP2 = false>
; __device__ __forceinline__ void gemm_phase(PG8_LAS unsigned char* lds, const Gemm g, const Sched& S, const Epi& E) {
;     ...
;             PG8_WAIT_V(8); PG8_WAIT_L(0); PG8_BAR; PG8_MMA(1, 0, At, B0); PG8_MMA(1, 1, At, B1); PG8_BAR; PG8_SCHED;
;             PG8_LDB(B0, 1, 0); PG8_LDB(B1, 1, 1); PG8_SCHED; PG8_LDA(At, 1, 0); PG8_STAGE(PG8_SA(0, 1), a2 + hstep, voffA);
;             PG8_WAIT_V(8); PG8_WAIT_L(0); PG8_BAR; PG8_MMA(0, 0, At, B0); PG8_MMA(0, 1, At, B1); PG8_BAR; PG8_SCHED;
	v_mfma_f32_16x16x32_bf16 v[62:65], v[152:155], v[184:187], v[62:65]
	v_mfma_f32_16x16x32_bf16 v[58:61], v[160:163], v[184:187], v[58:61]
	v_mfma_f32_16x16x32_bf16 v[46:49], v[152:155], v[192:195], v[46:49]
	v_mfma_f32_16x16x32_bf16 v[42:45], v[160:163], v[192:195], v[42:45]
	v_mfma_f32_16x16x32_bf16 v[30:33], v[152:155], v[204:207], v[30:33]
	v_mfma_f32_16x16x32_bf16 v[26:29], v[160:163], v[204:207], v[26:29]
	v_mfma_f32_16x16x32_bf16 v[14:17], v[152:155], v[212:215], v[14:17]
	v_mfma_f32_16x16x32_bf16 v[10:13], v[160:163], v[212:215], v[10:13]
	v_mfma_f32_16x16x32_bf16 v[62:65], v[156:159], v[188:191], v[62:65]
	v_mfma_f32_16x16x32_bf16 v[58:61], v[164:167], v[188:191], v[58:61]
	v_mfma_f32_16x16x32_bf16 v[46:49], v[156:159], v[200:203], v[46:49]
	v_mfma_f32_16x16x32_bf16 v[42:45], v[164:167], v[200:203], v[42:45]
	v_mfma_f32_16x16x32_bf16 v[30:33], v[156:159], v[208:211], v[30:33]
	v_mfma_f32_16x16x32_bf16 v[26:29], v[164:167], v[208:211], v[26:29]
	v_mfma_f32_16x16x32_bf16 v[14:17], v[156:159], v[216:219], v[14:17]
	v_mfma_f32_16x16x32_bf16 v[10:13], v[164:167], v[216:219], v[10:13]
	v_mfma_f32_16x16x32_bf16 v[54:57], v[168:171], v[184:187], v[54:57]
	v_mfma_f32_16x16x32_bf16 v[50:53], v[176:179], v[184:187], v[50:53]
	v_mfma_f32_16x16x32_bf16 v[38:41], v[168:171], v[192:195], v[38:41]
	v_mfma_f32_16x16x32_bf16 v[34:37], v[176:179], v[192:195], v[34:37]
	v_mfma_f32_16x16x32_bf16 v[22:25], v[168:171], v[204:207], v[22:25]
	v_mfma_f32_16x16x32_bf16 v[18:21], v[176:179], v[204:207], v[18:21]
	v_mfma_f32_16x16x32_bf16 v[6:9], v[168:171], v[212:215], v[6:9]
	v_mfma_f32_16x16x32_bf16 v[2:5], v[176:179], v[212:215], v[2:5]
	v_mfma_f32_16x16x32_bf16 v[54:57], v[172:175], v[188:191], v[54:57]
	v_mfma_f32_16x16x32_bf16 v[50:53], v[180:183], v[188:191], v[50:53]
	v_mfma_f32_16x16x32_bf16 v[38:41], v[172:175], v[200:203], v[38:41]
	v_mfma_f32_16x16x32_bf16 v[34:37], v[180:183], v[200:203], v[34:37]
	v_mfma_f32_16x16x32_bf16 v[22:25], v[172:175], v[208:211], v[22:25]
	v_mfma_f32_16x16x32_bf16 v[18:21], v[180:183], v[208:211], v[18:21]
	v_mfma_f32_16x16x32_bf16 v[6:9], v[172:175], v[216:219], v[6:9]
	v_mfma_f32_16x16x32_bf16 v[2:5], v[180:183], v[216:219], v[2:5]
	s_setprio 0
	s_barrier
	s_add_i32 s43, 0, 0x18000
	s_add_i32 s48, 0, 0x1c000
	v_add_u32_e32 v164, s43, v197
	v_add_u32_e32 v180, s48, v197
	ds_read_b128 v[152:155], v164
	ds_read_b128 v[156:159], v164 offset:1024
	ds_read_b128 v[160:163], v164 offset:2048
	ds_read_b128 v[164:167], v164 offset:3072
	ds_read_b128 v[168:171], v180
	ds_read_b128 v[172:175], v180 offset:1024
	ds_read_b128 v[176:179], v180 offset:2048
	ds_read_b128 v[180:183], v180 offset:3072
	s_add_u32 s26, s26, 0x80000
	s_addc_u32 s27, s27, 0
	s_mov_b32 m0, s35
	v_lshl_add_u64 v[228:229], s[26:27], 0, v[0:1]
	ds_read_b128 v[184:187], v199 offset:32768
	ds_read_b128 v[188:191], v199 offset:33792
	ds_read_b128 v[192:195], v199 offset:34816
	ds_read_b128 v[200:203], v199 offset:35840
	ds_read_b128 v[204:207], v199 offset:36864
	ds_read_b128 v[208:211], v199 offset:37888
	ds_read_b128 v[212:215], v199 offset:38912
	ds_read_b128 v[216:219], v199 offset:39936
	global_load_lds_dwordx4 v[228:229], off
	s_mov_b32 m0, s76
	v_lshl_add_u64 v[228:229], s[26:27], 0, v[126:127]
	global_load_lds_dwordx4 v[228:229], off
	s_waitcnt vmcnt(8) lgkmcnt(0)
	s_setprio 1
	s_barrier
	v_mfma_f32_16x16x32_bf16 v[144:147], v[152:155], v[184:187], v[144:147]
	v_mfma_f32_16x16x32_bf16 v[122:125], v[160:163], v[184:187], v[122:125]
	v_mfma_f32_16x16x32_bf16 v[110:113], v[152:155], v[192:195], v[110:113]
	v_mfma_f32_16x16x32_bf16 v[106:109], v[160:163], v[192:195], v[106:109]
	v_mfma_f32_16x16x32_bf16 v[94:97], v[152:155], v[204:207], v[94:97]
	v_mfma_f32_16x16x32_bf16 v[90:93], v[160:163], v[204:207], v[90:93]
	v_mfma_f32_16x16x32_bf16 v[78:81], v[152:155], v[212:215], v[78:81]
	v_mfma_f32_16x16x32_bf16 v[74:77], v[160:163], v[212:215], v[74:77]
	v_mfma_f32_16x16x32_bf16 v[144:147], v[156:159], v[188:191], v[144:147]
	v_mfma_f32_16x16x32_bf16 v[122:125], v[164:167], v[188:191], v[122:125]
	v_mfma_f32_16x16x32_bf16 v[110:113], v[156:159], v[200:203], v[110:113]
	v_mfma_f32_16x16x32_bf16 v[106:109], v[164:167], v[200:203], v[106:109]
	v_mfma_f32_16x16x32_bf16 v[94:97], v[156:159], v[208:211], v[94:97]
	v_mfma_f32_16x16x32_bf16 v[90:93], v[164:167], v[208:211], v[90:93]
	v_mfma_f32_16x16x32_bf16 v[78:81], v[156:159], v[216:219], v[78:81]
	v_mfma_f32_16x16x32_bf16 v[74:77], v[164:167], v[216:219], v[74:77]
	v_mfma_f32_16x16x32_bf16 v[118:121], v[168:171], v[184:187], v[118:121]
	v_mfma_f32_16x16x32_bf16 v[114:117], v[176:179], v[184:187], v[114:117]
	v_mfma_f32_16x16x32_bf16 v[102:105], v[168:171], v[192:195], v[102:105]
	v_mfma_f32_16x16x32_bf16 v[98:101], v[176:179], v[192:195], v[98:101]
	v_mfma_f32_16x16x32_bf16 v[86:89], v[168:171], v[204:207], v[86:89]
	v_mfma_f32_16x16x32_bf16 v[82:85], v[176:179], v[204:207], v[82:85]
	v_mfma_f32_16x16x32_bf16 v[70:73], v[168:171], v[212:215], v[70:73]
	v_mfma_f32_16x16x32_bf16 v[66:69], v[176:179], v[212:215], v[66:69]
	v_mfma_f32_16x16x32_bf16 v[118:121], v[172:175], v[188:191], v[118:121]
	v_mfma_f32_16x16x32_bf16 v[114:117], v[180:183], v[188:191], v[114:117]
	v_mfma_f32_16x16x32_bf16 v[102:105], v[172:175], v[200:203], v[102:105]
	v_mfma_f32_16x16x32_bf16 v[98:101], v[180:183], v[200:203], v[98:101]
	v_mfma_f32_16x16x32_bf16 v[86:89], v[172:175], v[208:211], v[86:89]
	v_mfma_f32_16x16x32_bf16 v[82:85], v[180:183], v[208:211], v[82:85]
	v_mfma_f32_16x16x32_bf16 v[70:73], v[172:175], v[216:219], v[70:73]
	v_mfma_f32_16x16x32_bf16 v[66:69], v[180:183], v[216:219], v[66:69]
	s_setprio 0
	s_barrier
; #define PG8_STAGE(bufoff, gbase, voff) do { _Pragma("unroll") for (int _i = 0; _i < 2; ++_i) \
;         __builtin_amdgcn_global_load_lds((const unsigned*)((const char*)(gbase) + (voff)[_i]), (PG8_LAS unsigned*)(lds + (bufoff) + ldsw + _i * 8192), 16, 0, 0); } while (0)
; #define PG8_LDA(dst, b, h) do { _Pragma("unroll") for (int m = 0; m < 4; ++m) _Pragma("unroll") for (int k = 0; k < 2; ++k) dst[m][k] = *(const PG8_LAS bf16x8*)(lds + PG8_SA(b, h) + aoff + m * 2048 + k * 1024); } while (0)
; #define PG8_MMA(ai, bj, At, Bt) do { __builtin_amdgcn_s_setprio(1); _Pragma("unroll") for (int m = 0; m < 4; ++m) _Pragma("unroll") for (int n = 0; n < 2; ++n) _Pragma("unroll") for (int k = 0; k < 2; ++k) \
;         acc[ai][bj][m][n] = __builtin_amdgcn_mfma_f32_16x16x32_bf16(Bt[n][k], At[m][k], acc[ai][bj][m][n], 0, 0, 0); __builtin_amdgcn_s_setprio(0); } while (0)
; #define PG8_WAIT_V(n) asm volatile("s_waitcnt vmcnt(" #n ")" ::: "memory")
; #define PG8_WAIT_L(n) asm volatile("s_waitcnt lgkmcnt(" #n ")" ::: "memory")
; #define PG8_BAR __builtin_amdgcn_s_barrier()
; #define PG8_SCHED __builtin_amdgcn_sched_barrier(0)
; template <class Epi, class Sched, bool ALIGN_EPI = false, bool SP2 = false>
; __device__ __forceinline__ void gemm_phase(PG8_LAS unsigned char* lds, const Gemm g, const Sched& S, const Epi& E) {
;     ...
;             PG8_LDA(At, 1, 1); PG8_STAGE(PG8_SB(1, 0), b3, voffB); PG8_STAGE(PG8_SB(1, 1), b3 + hstep, voffB); PG8_STAGE(PG8_SA(1, 0), a3, voffA);
;             PG8_WAIT_V(8); PG8_WAIT_L(0); PG8_BAR; PG8_MMA(1, 0, At, B0); PG8_MMA(1, 1, At, B1); PG8_BAR; PG8_SCHED;
;     ...
;         if constexpr (ALIGN_EPI) { if (wr == 0) PG8_BAR; }
	s_add_i32 s26, s43, s30
	v_lshl_add_u64 v[220:221], v[220:221], 0, s[64:65]
	s_mov_b32 m0, s26
	ds_read_b128 v[184:187], v199 offset:49152
	ds_read_b128 v[188:191], v199 offset:50176
	ds_read_b128 v[192:195], v199 offset:51200
	ds_read_b128 v[200:203], v199 offset:52224
	ds_read_b128 v[204:207], v199 offset:53248
	ds_read_b128 v[208:211], v199 offset:54272
	ds_read_b128 v[212:215], v199 offset:55296
	ds_read_b128 v[216:219], v199 offset:56320
	global_load_lds_dwordx4 v[220:221], off
	s_add_i32 m0, s26, 0x2000
	s_add_u32 s24, s24, 0x80080
	v_lshl_add_u64 v[220:221], v[222:223], 0, s[64:65]
	s_addc_u32 s25, s25, 0
	s_add_i32 s26, s48, s30
	global_load_lds_dwordx4 v[220:221], off
	s_mov_b32 m0, s26
	v_lshl_add_u64 v[220:221], s[24:25], 0, v[0:1]
	global_load_lds_dwordx4 v[220:221], off
	s_add_i32 m0, s26, 0x2000
	v_lshl_add_u64 v[220:221], s[24:25], 0, v[126:127]
	global_load_lds_dwordx4 v[220:221], off
	s_mov_b32 m0, s82
	v_lshl_add_u64 v[220:221], v[224:225], 0, s[64:65]
	global_load_lds_dwordx4 v[220:221], off
	s_mov_b32 m0, s83
	v_lshl_add_u64 v[220:221], v[226:227], 0, s[64:65]
	global_load_lds_dwordx4 v[220:221], off
	s_waitcnt vmcnt(8) lgkmcnt(0)
	s_setprio 1
	s_barrier
	v_mfma_f32_16x16x32_bf16 v[62:65], v[152:155], v[184:187], v[62:65]
	v_mfma_f32_16x16x32_bf16 v[58:61], v[160:163], v[184:187], v[58:61]
	v_mfma_f32_16x16x32_bf16 v[46:49], v[152:155], v[192:195], v[46:49]
	v_mfma_f32_16x16x32_bf16 v[42:45], v[160:163], v[192:195], v[42:45]
	v_mfma_f32_16x16x32_bf16 v[30:33], v[152:155], v[204:207], v[30:33]
	v_mfma_f32_16x16x32_bf16 v[26:29], v[160:163], v[204:207], v[26:29]
	v_mfma_f32_16x16x32_bf16 v[14:17], v[152:155], v[212:215], v[14:17]
	v_mfma_f32_16x16x32_bf16 v[10:13], v[160:163], v[212:215], v[10:13]
	v_mfma_f32_16x16x32_bf16 v[62:65], v[156:159], v[188:191], v[62:65]
	v_mfma_f32_16x16x32_bf16 v[58:61], v[164:167], v[188:191], v[58:61]
	v_mfma_f32_16x16x32_bf16 v[46:49], v[156:159], v[200:203], v[46:49]
	v_mfma_f32_16x16x32_bf16 v[42:45], v[164:167], v[200:203], v[42:45]
	v_mfma_f32_16x16x32_bf16 v[30:33], v[156:159], v[208:211], v[30:33]
	v_mfma_f32_16x16x32_bf16 v[26:29], v[164:167], v[208:211], v[26:29]
	v_mfma_f32_16x16x32_bf16 v[14:17], v[156:159], v[216:219], v[14:17]
	v_mfma_f32_16x16x32_bf16 v[10:13], v[164:167], v[216:219], v[10:13]
	v_mfma_f32_16x16x32_bf16 v[54:57], v[168:171], v[184:187], v[54:57]
	v_mfma_f32_16x16x32_bf16 v[50:53], v[176:179], v[184:187], v[50:53]
	v_mfma_f32_16x16x32_bf16 v[38:41], v[168:171], v[192:195], v[38:41]
	v_mfma_f32_16x16x32_bf16 v[34:37], v[176:179], v[192:195], v[34:37]
	v_mfma_f32_16x16x32_bf16 v[22:25], v[168:171], v[204:207], v[22:25]
	v_mfma_f32_16x16x32_bf16 v[18:21], v[176:179], v[204:207], v[18:21]
	v_mfma_f32_16x16x32_bf16 v[6:9], v[168:171], v[212:215], v[6:9]
	v_mfma_f32_16x16x32_bf16 v[2:5], v[176:179], v[212:215], v[2:5]
	v_mfma_f32_16x16x32_bf16 v[54:57], v[172:175], v[188:191], v[54:57]
	v_mfma_f32_16x16x32_bf16 v[50:53], v[180:183], v[188:191], v[50:53]
	v_mfma_f32_16x16x32_bf16 v[38:41], v[172:175], v[200:203], v[38:41]
	v_mfma_f32_16x16x32_bf16 v[34:37], v[180:183], v[200:203], v[34:37]
	v_mfma_f32_16x16x32_bf16 v[22:25], v[172:175], v[208:211], v[22:25]
	v_mfma_f32_16x16x32_bf16 v[18:21], v[180:183], v[208:211], v[18:21]
	v_mfma_f32_16x16x32_bf16 v[6:9], v[172:175], v[216:219], v[6:9]
	v_mfma_f32_16x16x32_bf16 v[2:5], v[180:183], v[216:219], v[2:5]
	s_setprio 0
	s_barrier
	s_add_i32 s42, s42, 2
	s_add_u32 s0, s0, 0x100
	s_addc_u32 s1, s1, 0
	s_add_u32 s40, s40, 0x100
	s_addc_u32 s41, s41, 0
	s_cmp_gt_u32 s42, 29
	s_cbranch_scc0 .LBB0_963
	s_and_b64 vcc, exec, s[14:15]
	s_cbranch_vccz .LBB0_966
	s_barrier
